# ctx split-K ffn-down epilogue: quad 4x4 DPP transpose so each f32 atomic wave-instr covers 4 rows x 64B (4 line requests instead of 16)
# speedup vs baseline: 1.0558x; 1.0558x over previous
; #define PG8_STAGE(bufoff, gbase, voff) do { _Pragma("unroll") for (int _i = 0; _i < 2; ++_i) \
;         __builtin_amdgcn_global_load_lds((const unsigned*)((const char*)(gbase) + (voff)[_i]), (PG8_LAS unsigned*)(lds + (bufoff) + ldsw + _i * 8192), 16, 0, 0); } while (0)
; #define PG8_LDA(dst, b, h) do { _Pragma("unroll") for (int m = 0; m < 4; ++m) _Pragma("unroll") for (int k = 0; k < 2; ++k) dst[m][k] = *(const PG8_LAS bf16x8*)(lds + PG8_SA(b, h) + aoff + m * 2048 + k * 1024); } while (0)
; #define PG8_LDB(dst, b, h) do { _Pragma("unroll") for (int n = 0; n < 2; ++n) _Pragma("unroll") for (int k = 0; k < 2; ++k) dst[n][k] = *(const PG8_LAS bf16x8*)(lds + PG8_SB(b, h) + boff + n * 2048 + k * 1024); } while (0)
; #define PG8_MMA(ai, bj, At, Bt) do { __builtin_amdgcn_s_setprio(1); _Pragma("unroll") for (int m = 0; m < 4; ++m) _Pragma("unroll") for (int n = 0; n < 2; ++n) _Pragma("unroll") for (int k = 0; k < 2; ++k) \
;         acc[ai][bj][m][n] = __builtin_amdgcn_mfma_f32_16x16x32_bf16(Bt[n][k], At[m][k], acc[ai][bj][m][n], 0, 0, 0); __builtin_amdgcn_s_setprio(0); } while (0)
; #define PG8_WAIT_L(n) asm volatile("s_waitcnt lgkmcnt(" #n ")" ::: "memory")
; #define PG8_BAR __builtin_amdgcn_s_barrier()
; #define PG8_SCHED __builtin_amdgcn_sched_barrier(0)
; template <class Epi>
; __device__ __forceinline__ void gemm_phase(PG8_LAS unsigned char* lds, const GemmD g, const Epi& E) {
;     ...
;         for (int t = 0; t < nt; t += 2) {
;             const bool last = (t == nt - 2);
;             const char* a1 = cA + (size_t)(t + 1) * kstep;
;             const char* a2 = last ? nA : cA + (size_t)(t + 2) * kstep; const char* b2 = last ? nB : cB + (size_t)(t + 2) * kstep;
;             const char* a3 = a2 + kstep; const char* b3 = b2 + kstep;
;             PG8_LDB(B0, 0, 0); PG8_SCHED; PG8_LDA(At, 0, 0); PG8_STAGE(PG8_SA(1, 1), a1 + hstepA, voffA);
;             PG8_WAIT_L(8); PG8_BAR; PG8_WAIT_L(0); PG8_MMA(0, 0, At, B0); PG8_BAR; PG8_SCHED;
;             PG8_LDB(B1, 0, 1); PG8_STAGE(PG8_SB(0, 0), b2, voffB);
;             PG8_BAR; PG8_WAIT_L(0); PG8_MMA(0, 1, At, B1); PG8_BAR;
;             PG8_LDA(At, 0, 1); PG8_STAGE(PG8_SA(0, 0), a2, voffA);
;             PG8_BAR; PG8_WAIT_L(0); PG8_MMA(1, 0, At, B0); PG8_BAR; PG8_SCHED;
.LBB0_376:
	s_add_u32 s59, s18, s58
	s_addc_u32 s60, s19, 0
	s_add_u32 s61, s59, 0x100
	s_addc_u32 s62, s60, 0
	s_and_b64 s[24:25], s[22:23], exec
	ds_read_b128 v[134:137], v158
	ds_read_b128 v[138:141], v158 offset:1024
	ds_read_b128 v[148:151], v158 offset:2048
	ds_read_b128 v[152:155], v158 offset:3072
	s_cselect_b32 s25, s13, s62
	s_cselect_b32 s24, s12, s61
	s_add_u32 s58, s16, s58
	s_addc_u32 s61, s17, 0
	s_add_u32 s58, s58, 0x100
	s_addc_u32 s61, s61, 0
	s_and_b64 s[22:23], s[22:23], exec
	s_cselect_b32 s23, s1, s61
	s_cselect_b32 s22, s0, s58
	s_add_u32 s58, s59, 0xb0080
	s_addc_u32 s59, s60, 0
	s_mov_b32 m0, s48
	v_lshl_add_u64 v[142:143], s[58:59], 0, v[144:145]
	ds_read_b128 v[164:167], v159
	ds_read_b128 v[172:175], v159 offset:1024
	ds_read_b128 v[176:179], v159 offset:2048
	ds_read_b128 v[180:183], v159 offset:3072
	ds_read_b128 v[184:187], v159 offset:4096
	ds_read_b128 v[188:191], v159 offset:5120
	ds_read_b128 v[192:195], v159 offset:6144
	ds_read_b128 v[196:199], v159 offset:7168
	global_load_lds_dwordx4 v[142:143], off
	v_lshl_add_u64 v[142:143], s[58:59], 0, v[146:147]
	s_mov_b32 m0, s49
	s_nop 0
	global_load_lds_dwordx4 v[142:143], off
	s_waitcnt lgkmcnt(8)
	s_barrier
	s_waitcnt lgkmcnt(0)
	s_setprio 1
	s_waitcnt lgkmcnt(0)
	v_mfma_f32_16x16x32_bf16 v[124:127], v[134:137], v[164:167], v[124:127]
	v_mfma_f32_16x16x32_bf16 v[92:95], v[148:151], v[164:167], v[92:95]
	v_mfma_f32_16x16x32_bf16 v[120:123], v[134:137], v[176:179], v[120:123]
	v_mfma_f32_16x16x32_bf16 v[88:91], v[148:151], v[176:179], v[88:91]
	v_mfma_f32_16x16x32_bf16 v[116:119], v[134:137], v[184:187], v[116:119]
	v_mfma_f32_16x16x32_bf16 v[84:87], v[148:151], v[184:187], v[84:87]
	v_mfma_f32_16x16x32_bf16 v[112:115], v[134:137], v[192:195], v[112:115]
	v_mfma_f32_16x16x32_bf16 v[80:83], v[148:151], v[192:195], v[80:83]
	v_mfma_f32_16x16x32_bf16 v[124:127], v[138:141], v[172:175], v[124:127]
	v_mfma_f32_16x16x32_bf16 v[92:95], v[152:155], v[172:175], v[92:95]
	v_mfma_f32_16x16x32_bf16 v[120:123], v[138:141], v[180:183], v[120:123]
	v_mfma_f32_16x16x32_bf16 v[88:91], v[152:155], v[180:183], v[88:91]
	v_mfma_f32_16x16x32_bf16 v[116:119], v[138:141], v[188:191], v[116:119]
	v_mfma_f32_16x16x32_bf16 v[84:87], v[152:155], v[188:191], v[84:87]
	v_mfma_f32_16x16x32_bf16 v[112:115], v[138:141], v[196:199], v[112:115]
	v_mfma_f32_16x16x32_bf16 v[80:83], v[152:155], v[196:199], v[80:83]
	s_setprio 0
	s_barrier
	s_mov_b32 m0, s50
	v_lshl_add_u64 v[142:143], s[22:23], 0, v[144:145]
	ds_read_b128 v[200:203], v160
	ds_read_b128 v[204:207], v160 offset:1024
	ds_read_b128 v[208:211], v160 offset:2048
	ds_read_b128 v[212:215], v160 offset:3072
	global_load_lds_dwordx4 v[142:143], off
	v_lshl_add_u64 v[216:217], s[22:23], 0, v[146:147]
	s_mov_b32 m0, s51
	s_nop 0
	global_load_lds_dwordx4 v[216:217], off
	s_barrier
	s_waitcnt lgkmcnt(0)
	s_setprio 1
	s_waitcnt lgkmcnt(0)
	v_mfma_f32_16x16x32_bf16 v[60:63], v[200:203], v[164:167], v[60:63]
	v_mfma_f32_16x16x32_bf16 v[40:43], v[208:211], v[164:167], v[40:43]
	v_mfma_f32_16x16x32_bf16 v[56:59], v[200:203], v[176:179], v[56:59]
	v_mfma_f32_16x16x32_bf16 v[32:35], v[208:211], v[176:179], v[32:35]
	v_mfma_f32_16x16x32_bf16 v[52:55], v[200:203], v[184:187], v[52:55]
	v_mfma_f32_16x16x32_bf16 v[24:27], v[208:211], v[184:187], v[24:27]
	v_mfma_f32_16x16x32_bf16 v[48:51], v[200:203], v[192:195], v[48:51]
	v_mfma_f32_16x16x32_bf16 v[16:19], v[208:211], v[192:195], v[16:19]
	v_mfma_f32_16x16x32_bf16 v[60:63], v[204:207], v[172:175], v[60:63]
	v_mfma_f32_16x16x32_bf16 v[40:43], v[212:215], v[172:175], v[40:43]
	v_mfma_f32_16x16x32_bf16 v[56:59], v[204:207], v[180:183], v[56:59]
	v_mfma_f32_16x16x32_bf16 v[32:35], v[212:215], v[180:183], v[32:35]
	v_mfma_f32_16x16x32_bf16 v[52:55], v[204:207], v[188:191], v[52:55]
	v_mfma_f32_16x16x32_bf16 v[24:27], v[212:215], v[188:191], v[24:27]
	v_mfma_f32_16x16x32_bf16 v[48:51], v[204:207], v[196:199], v[48:51]
	v_mfma_f32_16x16x32_bf16 v[16:19], v[212:215], v[196:199], v[16:19]
	s_setprio 0
	s_mov_b32 m0, s34
	v_lshl_add_u64 v[218:219], s[24:25], 0, v[144:145]
	s_barrier
	ds_read_b128 v[164:167], v159 offset:16384
	ds_read_b128 v[172:175], v159 offset:17408
	ds_read_b128 v[176:179], v159 offset:18432
	ds_read_b128 v[180:183], v159 offset:19456
	ds_read_b128 v[184:187], v159 offset:20480
	ds_read_b128 v[188:191], v159 offset:21504
	ds_read_b128 v[192:195], v159 offset:22528
	ds_read_b128 v[196:199], v159 offset:23552
	global_load_lds_dwordx4 v[218:219], off
	v_lshl_add_u64 v[220:221], s[24:25], 0, v[146:147]
	s_mov_b32 m0, s35
	s_nop 0
	global_load_lds_dwordx4 v[220:221], off
	s_barrier
	s_waitcnt lgkmcnt(0)
	s_setprio 1
	s_waitcnt lgkmcnt(0)
	v_mfma_f32_16x16x32_bf16 v[108:111], v[134:137], v[164:167], v[108:111]
	v_mfma_f32_16x16x32_bf16 v[76:79], v[148:151], v[164:167], v[76:79]
	v_mfma_f32_16x16x32_bf16 v[104:107], v[134:137], v[176:179], v[104:107]
	v_mfma_f32_16x16x32_bf16 v[72:75], v[148:151], v[176:179], v[72:75]
	v_mfma_f32_16x16x32_bf16 v[100:103], v[134:137], v[184:187], v[100:103]
	v_mfma_f32_16x16x32_bf16 v[68:71], v[148:151], v[184:187], v[68:71]
	v_mfma_f32_16x16x32_bf16 v[96:99], v[134:137], v[192:195], v[96:99]
	v_mfma_f32_16x16x32_bf16 v[64:67], v[148:151], v[192:195], v[64:67]
	v_mfma_f32_16x16x32_bf16 v[108:111], v[138:141], v[172:175], v[108:111]
	v_mfma_f32_16x16x32_bf16 v[76:79], v[152:155], v[172:175], v[76:79]
	v_mfma_f32_16x16x32_bf16 v[104:107], v[138:141], v[180:183], v[104:107]
	v_mfma_f32_16x16x32_bf16 v[72:75], v[152:155], v[180:183], v[72:75]
	v_mfma_f32_16x16x32_bf16 v[100:103], v[138:141], v[188:191], v[100:103]
	v_mfma_f32_16x16x32_bf16 v[68:71], v[152:155], v[188:191], v[68:71]
	v_mfma_f32_16x16x32_bf16 v[96:99], v[138:141], v[196:199], v[96:99]
	v_mfma_f32_16x16x32_bf16 v[64:67], v[152:155], v[196:199], v[64:67]
	s_setprio 0
	s_barrier
; #define PG8_STAGE(bufoff, gbase, voff) do { _Pragma("unroll") for (int _i = 0; _i < 2; ++_i) \
;         __builtin_amdgcn_global_load_lds((const unsigned*)((const char*)(gbase) + (voff)[_i]), (PG8_LAS unsigned*)(lds + (bufoff) + ldsw + _i * 8192), 16, 0, 0); } while (0)
; #define PG8_LDA(dst, b, h) do { _Pragma("unroll") for (int m = 0; m < 4; ++m) _Pragma("unroll") for (int k = 0; k < 2; ++k) dst[m][k] = *(const PG8_LAS bf16x8*)(lds + PG8_SA(b, h) + aoff + m * 2048 + k * 1024); } while (0)
; #define PG8_LDB(dst, b, h) do { _Pragma("unroll") for (int n = 0; n < 2; ++n) _Pragma("unroll") for (int k = 0; k < 2; ++k) dst[n][k] = *(const PG8_LAS bf16x8*)(lds + PG8_SB(b, h) + boff + n * 2048 + k * 1024); } while (0)
; #define PG8_MMA(ai, bj, At, Bt) do { __builtin_amdgcn_s_setprio(1); _Pragma("unroll") for (int m = 0; m < 4; ++m) _Pragma("unroll") for (int n = 0; n < 2; ++n) _Pragma("unroll") for (int k = 0; k < 2; ++k) \
;         acc[ai][bj][m][n] = __builtin_amdgcn_mfma_f32_16x16x32_bf16(Bt[n][k], At[m][k], acc[ai][bj][m][n], 0, 0, 0); __builtin_amdgcn_s_setprio(0); } while (0)
; #define PG8_WAIT_V(n) asm volatile("s_waitcnt vmcnt(" #n ")" ::: "memory")
; #define PG8_WAIT_L(n) asm volatile("s_waitcnt lgkmcnt(" #n ")" ::: "memory")
; #define PG8_BAR __builtin_amdgcn_s_barrier()
; #define PG8_SCHED __builtin_amdgcn_sched_barrier(0)
; template <class Epi>
; __device__ __forceinline__ void gemm_phase(PG8_LAS unsigned char* lds, const GemmD g, const Epi& E) {
;     ...
;             PG8_STAGE(PG8_SB(0, 1), b2 + hstepB, voffB);
;             PG8_WAIT_V(6); PG8_BAR; PG8_MMA(1, 1, At, B1); PG8_BAR;
;             PG8_LDB(B0, 1, 0); PG8_SCHED; PG8_LDA(At, 1, 0); PG8_STAGE(PG8_SA(0, 1), a2 + hstepA, voffA);
;             PG8_WAIT_L(8); PG8_BAR; PG8_WAIT_L(0); PG8_MMA(0, 0, At, B0); PG8_BAR; PG8_SCHED;
;             PG8_LDB(B1, 1, 1); PG8_STAGE(PG8_SB(1, 0), b3, voffB);
;             PG8_BAR; PG8_WAIT_L(0); PG8_MMA(0, 1, At, B1); PG8_BAR;
;             PG8_LDA(At, 1, 1); PG8_STAGE(PG8_SA(1, 0), a3, voffA);
;             PG8_BAR; PG8_WAIT_L(0); PG8_MMA(1, 0, At, B0); PG8_BAR; PG8_SCHED;
	s_add_u32 s58, s22, 0xb0000
	s_addc_u32 s59, s23, 0
	s_mov_b32 m0, s52
	v_lshl_add_u64 v[134:135], s[58:59], 0, v[144:145]
	global_load_lds_dwordx4 v[134:135], off
	v_lshl_add_u64 v[134:135], s[58:59], 0, v[146:147]
	s_mov_b32 m0, s53
	s_nop 0
	global_load_lds_dwordx4 v[134:135], off
	s_waitcnt vmcnt(6)
	s_barrier
	s_setprio 1
	v_mfma_f32_16x16x32_bf16 v[44:47], v[200:203], v[164:167], v[44:47]
	v_mfma_f32_16x16x32_bf16 v[12:15], v[208:211], v[164:167], v[12:15]
	v_mfma_f32_16x16x32_bf16 v[36:39], v[200:203], v[176:179], v[36:39]
	v_mfma_f32_16x16x32_bf16 v[8:11], v[208:211], v[176:179], v[8:11]
	v_mfma_f32_16x16x32_bf16 v[28:31], v[200:203], v[184:187], v[28:31]
	v_mfma_f32_16x16x32_bf16 v[4:7], v[208:211], v[184:187], v[4:7]
	v_mfma_f32_16x16x32_bf16 v[20:23], v[200:203], v[192:195], v[20:23]
	v_mfma_f32_16x16x32_bf16 v[0:3], v[208:211], v[192:195], v[0:3]
	v_mfma_f32_16x16x32_bf16 v[44:47], v[204:207], v[172:175], v[44:47]
	v_mfma_f32_16x16x32_bf16 v[12:15], v[212:215], v[172:175], v[12:15]
	v_mfma_f32_16x16x32_bf16 v[36:39], v[204:207], v[180:183], v[36:39]
	v_mfma_f32_16x16x32_bf16 v[8:11], v[212:215], v[180:183], v[8:11]
	v_mfma_f32_16x16x32_bf16 v[28:31], v[204:207], v[188:191], v[28:31]
	v_mfma_f32_16x16x32_bf16 v[4:7], v[212:215], v[188:191], v[4:7]
	v_mfma_f32_16x16x32_bf16 v[20:23], v[204:207], v[196:199], v[20:23]
	v_mfma_f32_16x16x32_bf16 v[0:3], v[212:215], v[196:199], v[0:3]
	s_setprio 0
	s_barrier
	ds_read_b128 v[134:137], v161
	ds_read_b128 v[138:141], v161 offset:1024
	ds_read_b128 v[148:151], v161 offset:2048
	ds_read_b128 v[152:155], v161 offset:3072
	s_add_u32 s24, s24, 0xb0000
	s_addc_u32 s25, s25, 0
	s_mov_b32 m0, s36
	v_lshl_add_u64 v[200:201], s[24:25], 0, v[144:145]
	ds_read_b128 v[164:167], v159 offset:32768
	ds_read_b128 v[172:175], v159 offset:33792
	ds_read_b128 v[176:179], v159 offset:34816
	ds_read_b128 v[180:183], v159 offset:35840
	ds_read_b128 v[184:187], v159 offset:36864
	ds_read_b128 v[188:191], v159 offset:37888
	ds_read_b128 v[192:195], v159 offset:38912
	ds_read_b128 v[196:199], v159 offset:39936
	global_load_lds_dwordx4 v[200:201], off
	v_lshl_add_u64 v[200:201], s[24:25], 0, v[146:147]
	s_mov_b32 m0, s37
	s_nop 0
	global_load_lds_dwordx4 v[200:201], off
	s_waitcnt lgkmcnt(8)
	s_barrier
	s_waitcnt lgkmcnt(0)
	s_setprio 1
	s_waitcnt lgkmcnt(0)
	v_mfma_f32_16x16x32_bf16 v[124:127], v[134:137], v[164:167], v[124:127]
	v_mfma_f32_16x16x32_bf16 v[92:95], v[148:151], v[164:167], v[92:95]
	v_mfma_f32_16x16x32_bf16 v[120:123], v[134:137], v[176:179], v[120:123]
	v_mfma_f32_16x16x32_bf16 v[88:91], v[148:151], v[176:179], v[88:91]
	v_mfma_f32_16x16x32_bf16 v[116:119], v[134:137], v[184:187], v[116:119]
	v_mfma_f32_16x16x32_bf16 v[84:87], v[148:151], v[184:187], v[84:87]
	v_mfma_f32_16x16x32_bf16 v[112:115], v[134:137], v[192:195], v[112:115]
	v_mfma_f32_16x16x32_bf16 v[80:83], v[148:151], v[192:195], v[80:83]
	v_mfma_f32_16x16x32_bf16 v[124:127], v[138:141], v[172:175], v[124:127]
	v_mfma_f32_16x16x32_bf16 v[92:95], v[152:155], v[172:175], v[92:95]
	v_mfma_f32_16x16x32_bf16 v[120:123], v[138:141], v[180:183], v[120:123]
	v_mfma_f32_16x16x32_bf16 v[88:91], v[152:155], v[180:183], v[88:91]
	v_mfma_f32_16x16x32_bf16 v[116:119], v[138:141], v[188:191], v[116:119]
	v_mfma_f32_16x16x32_bf16 v[84:87], v[152:155], v[188:191], v[84:87]
	v_mfma_f32_16x16x32_bf16 v[112:115], v[138:141], v[196:199], v[112:115]
	v_mfma_f32_16x16x32_bf16 v[80:83], v[152:155], v[196:199], v[80:83]
	s_setprio 0
	s_barrier
	s_mov_b32 m0, s55
	v_lshl_add_u64 v[142:143], v[142:143], 0, s[6:7]
	ds_read_b128 v[200:203], v162
	ds_read_b128 v[204:207], v162 offset:1024
	ds_read_b128 v[208:211], v162 offset:2048
	ds_read_b128 v[212:215], v162 offset:3072
	global_load_lds_dwordx4 v[142:143], off
	v_lshl_add_u64 v[142:143], v[216:217], 0, s[6:7]
	s_add_i32 m0, s55, 0x2000
	s_nop 0
	global_load_lds_dwordx4 v[142:143], off
	s_barrier
	s_waitcnt lgkmcnt(0)
	s_setprio 1
	s_waitcnt lgkmcnt(0)
	v_mfma_f32_16x16x32_bf16 v[60:63], v[200:203], v[164:167], v[60:63]
	v_mfma_f32_16x16x32_bf16 v[40:43], v[208:211], v[164:167], v[40:43]
	v_mfma_f32_16x16x32_bf16 v[56:59], v[200:203], v[176:179], v[56:59]
	v_mfma_f32_16x16x32_bf16 v[32:35], v[208:211], v[176:179], v[32:35]
	v_mfma_f32_16x16x32_bf16 v[52:55], v[200:203], v[184:187], v[52:55]
	v_mfma_f32_16x16x32_bf16 v[24:27], v[208:211], v[184:187], v[24:27]
	v_mfma_f32_16x16x32_bf16 v[48:51], v[200:203], v[192:195], v[48:51]
	v_mfma_f32_16x16x32_bf16 v[16:19], v[208:211], v[192:195], v[16:19]
	v_mfma_f32_16x16x32_bf16 v[60:63], v[204:207], v[172:175], v[60:63]
	v_mfma_f32_16x16x32_bf16 v[40:43], v[212:215], v[172:175], v[40:43]
	v_mfma_f32_16x16x32_bf16 v[56:59], v[204:207], v[180:183], v[56:59]
	v_mfma_f32_16x16x32_bf16 v[32:35], v[212:215], v[180:183], v[32:35]
	v_mfma_f32_16x16x32_bf16 v[52:55], v[204:207], v[188:191], v[52:55]
	v_mfma_f32_16x16x32_bf16 v[24:27], v[212:215], v[188:191], v[24:27]
	v_mfma_f32_16x16x32_bf16 v[48:51], v[204:207], v[196:199], v[48:51]
	v_mfma_f32_16x16x32_bf16 v[16:19], v[212:215], v[196:199], v[16:19]
	s_setprio 0
	s_mov_b32 m0, s40
	v_lshl_add_u64 v[142:143], v[218:219], 0, s[6:7]
	s_barrier
	ds_read_b128 v[164:167], v159 offset:49152
	ds_read_b128 v[172:175], v159 offset:50176
	ds_read_b128 v[176:179], v159 offset:51200
	ds_read_b128 v[180:183], v159 offset:52224
	ds_read_b128 v[184:187], v159 offset:53248
	ds_read_b128 v[188:191], v159 offset:54272
	ds_read_b128 v[192:195], v159 offset:55296
	ds_read_b128 v[196:199], v159 offset:56320
	global_load_lds_dwordx4 v[142:143], off
	v_lshl_add_u64 v[142:143], v[220:221], 0, s[6:7]
	s_mov_b32 m0, s41
	s_nop 0
	global_load_lds_dwordx4 v[142:143], off
	s_barrier
; #define PG8_STAGE(bufoff, gbase, voff) do { _Pragma("unroll") for (int _i = 0; _i < 2; ++_i) \
;         __builtin_amdgcn_global_load_lds((const unsigned*)((const char*)(gbase) + (voff)[_i]), (PG8_LAS unsigned*)(lds + (bufoff) + ldsw + _i * 8192), 16, 0, 0); } while (0)
; #define PG8_MMA(ai, bj, At, Bt) do { __builtin_amdgcn_s_setprio(1); _Pragma("unroll") for (int m = 0; m < 4; ++m) _Pragma("unroll") for (int n = 0; n < 2; ++n) _Pragma("unroll") for (int k = 0; k < 2; ++k) \
;         acc[ai][bj][m][n] = __builtin_amdgcn_mfma_f32_16x16x32_bf16(Bt[n][k], At[m][k], acc[ai][bj][m][n], 0, 0, 0); __builtin_amdgcn_s_setprio(0); } while (0)
; #define PG8_WAIT_V(n) asm volatile("s_waitcnt vmcnt(" #n ")" ::: "memory")
; #define PG8_WAIT_L(n) asm volatile("s_waitcnt lgkmcnt(" #n ")" ::: "memory")
; #define PG8_BAR __builtin_amdgcn_s_barrier()
; #define PG8_SCHED __builtin_amdgcn_sched_barrier(0)
; template <class Epi>
; __device__ __forceinline__ void gemm_phase(PG8_LAS unsigned char* lds, const GemmD g, const Epi& E) {
;     ...
;             PG8_BAR; PG8_WAIT_L(0); PG8_MMA(1, 0, At, B0); PG8_BAR; PG8_SCHED;
;             PG8_STAGE(PG8_SB(1, 1), b3 + hstepB, voffB);
;             PG8_WAIT_V(6); PG8_BAR; PG8_MMA(1, 1, At, B1); PG8_BAR;
;     __device__ __forceinline__ void operator()(const AccT& acc, const Unit& u, int wr, int wc, int fr, int fq) const {
; #pragma unroll
;         for (int bj = 0; bj < 2; ++bj)
; #pragma unroll
;             for (int nn = 0; nn < 2; ++nn) {
;                 const int n = 256 * u.pn + 128 * bj + 32 * wc + 16 * nn + 4 * fq;
;                 const f32x4 gt = *(const f32x4*)(mod + 4 * 9216 + 2 * 1024 + n) * 0.5f;
;                 float* xb = XR + (size_t)(256 * u.pm + 64 * wr + fr) * 1024 + n;
	s_waitcnt lgkmcnt(0)
	s_setprio 1
	s_waitcnt lgkmcnt(0)
	v_mfma_f32_16x16x32_bf16 v[108:111], v[134:137], v[164:167], v[108:111]
	v_mfma_f32_16x16x32_bf16 v[76:79], v[148:151], v[164:167], v[76:79]
	v_mfma_f32_16x16x32_bf16 v[104:107], v[134:137], v[176:179], v[104:107]
	v_mfma_f32_16x16x32_bf16 v[72:75], v[148:151], v[176:179], v[72:75]
	v_mfma_f32_16x16x32_bf16 v[100:103], v[134:137], v[184:187], v[100:103]
	v_mfma_f32_16x16x32_bf16 v[68:71], v[148:151], v[184:187], v[68:71]
	v_mfma_f32_16x16x32_bf16 v[96:99], v[134:137], v[192:195], v[96:99]
	v_mfma_f32_16x16x32_bf16 v[64:67], v[148:151], v[192:195], v[64:67]
	v_mfma_f32_16x16x32_bf16 v[108:111], v[138:141], v[172:175], v[108:111]
	v_mfma_f32_16x16x32_bf16 v[76:79], v[152:155], v[172:175], v[76:79]
	v_mfma_f32_16x16x32_bf16 v[104:107], v[138:141], v[180:183], v[104:107]
	v_mfma_f32_16x16x32_bf16 v[72:75], v[152:155], v[180:183], v[72:75]
	v_mfma_f32_16x16x32_bf16 v[100:103], v[138:141], v[188:191], v[100:103]
	v_mfma_f32_16x16x32_bf16 v[68:71], v[152:155], v[188:191], v[68:71]
	v_mfma_f32_16x16x32_bf16 v[96:99], v[138:141], v[196:199], v[96:99]
	v_mfma_f32_16x16x32_bf16 v[64:67], v[152:155], v[196:199], v[64:67]
	s_setprio 0
	s_barrier
	s_add_u32 s22, s22, 0xb0080
	s_addc_u32 s23, s23, 0
	s_add_i32 s24, s54, s31
	v_lshl_add_u64 v[134:135], s[22:23], 0, v[144:145]
	s_mov_b32 m0, s24
	s_nop 0
	global_load_lds_dwordx4 v[134:135], off
	v_lshl_add_u64 v[134:135], s[22:23], 0, v[146:147]
	s_add_i32 m0, s24, 0x2000
	s_nop 0
	global_load_lds_dwordx4 v[134:135], off
	s_waitcnt vmcnt(6)
	s_barrier
	s_setprio 1
	v_mfma_f32_16x16x32_bf16 v[44:47], v[200:203], v[164:167], v[44:47]
	v_mfma_f32_16x16x32_bf16 v[12:15], v[208:211], v[164:167], v[12:15]
	v_mfma_f32_16x16x32_bf16 v[36:39], v[200:203], v[176:179], v[36:39]
	v_mfma_f32_16x16x32_bf16 v[8:11], v[208:211], v[176:179], v[8:11]
	v_mfma_f32_16x16x32_bf16 v[28:31], v[200:203], v[184:187], v[28:31]
	v_mfma_f32_16x16x32_bf16 v[4:7], v[208:211], v[184:187], v[4:7]
	v_mfma_f32_16x16x32_bf16 v[20:23], v[200:203], v[192:195], v[20:23]
	v_mfma_f32_16x16x32_bf16 v[0:3], v[208:211], v[192:195], v[0:3]
	v_mfma_f32_16x16x32_bf16 v[44:47], v[204:207], v[172:175], v[44:47]
	v_mfma_f32_16x16x32_bf16 v[12:15], v[212:215], v[172:175], v[12:15]
	v_mfma_f32_16x16x32_bf16 v[36:39], v[204:207], v[180:183], v[36:39]
	v_mfma_f32_16x16x32_bf16 v[8:11], v[212:215], v[180:183], v[8:11]
	v_mfma_f32_16x16x32_bf16 v[28:31], v[204:207], v[188:191], v[28:31]
	v_mfma_f32_16x16x32_bf16 v[4:7], v[212:215], v[188:191], v[4:7]
	v_mfma_f32_16x16x32_bf16 v[20:23], v[204:207], v[196:199], v[20:23]
	v_mfma_f32_16x16x32_bf16 v[0:3], v[212:215], v[196:199], v[0:3]
	s_setprio 0
	s_movk_i32 s58, 0x100
	s_and_b64 vcc, exec, s[20:21]
	s_mov_b64 s[22:23], -1
	s_mov_b64 s[20:21], 0
	s_barrier
	s_cbranch_vccnz .LBB0_376
	v_lshl_add_u32 v128, s56, 8, v156
	v_lshl_or_b32 v154, s57, 8, v157
	v_mov_b32_e32 v155, v129
	s_and_b32 s57, s14, 3
	s_mov_b32 s56, s15
	v_and_or_b32 v154, v128, 3, v154
	v_and_or_b32 v128, v128, -4, 1
	s_mov_b64 s[16:17], s[0:1]
	s_mov_b64 s[18:19], s[12:13]
	v_lshlrev_b64 v[134:135], 2, v[154:155]
	v_lshl_add_u64 v[136:137], s[10:11], 0, v[134:135]
	global_load_dword v163, v[136:137], off
	global_load_dword v164, v[136:137], off offset:64
	global_load_dword v165, v[136:137], off offset:512
	global_load_dword v166, v[136:137], off offset:576
	v_lshlrev_b64 v[136:137], 12, v[128:129]
	v_lshl_add_u64 v[136:137], s[4:5], 0, v[136:137]
	v_lshl_add_u64 v[152:153], v[136:137], 0, v[134:135]
	v_add_co_u32_e32 v150, vcc, s39, v152
	s_nop 1
	v_addc_co_u32_e32 v151, vcc, 0, v153, vcc
	v_add_co_u32_e32 v148, vcc, s42, v152
	s_nop 1
	v_addc_co_u32_e32 v149, vcc, 0, v153, vcc
	v_add_co_u32_e32 v142, vcc, s43, v152
	s_nop 1
	v_addc_co_u32_e32 v143, vcc, 0, v153, vcc
	v_add_co_u32_e32 v140, vcc, s44, v152
	s_nop 1
	v_addc_co_u32_e32 v141, vcc, 0, v153, vcc
	v_add_co_u32_e32 v138, vcc, s45, v152
	s_nop 1
	v_addc_co_u32_e32 v139, vcc, 0, v153, vcc
	v_add_co_u32_e32 v136, vcc, s46, v152
	s_nop 1
	v_addc_co_u32_e32 v137, vcc, 0, v153, vcc
	v_add_co_u32_e32 v134, vcc, s47, v152
	s_nop 1
	v_addc_co_u32_e32 v135, vcc, 0, v153, vcc
	s_mov_b32 s98, 0x2000
	s_mov_b32 s99, 0
	s_mov_b32 s100, 0xffffe000
	s_mov_b32 s101, -1
	s_waitcnt vmcnt(0)
;     __device__ __forceinline__ void operator()(const AccT& acc, const Unit& u, int wr, int wc, int fr, int fq) const {
; #pragma unroll
;         for (int bj = 0; bj < 2; ++bj)
; #pragma unroll
;             for (int nn = 0; nn < 2; ++nn) {
;                 const int n = 256 * u.pn + 128 * bj + 32 * wc + 16 * nn + 4 * fq;
;                 const f32x4 gt = *(const f32x4*)(mod + 4 * 9216 + 2 * 1024 + n) * 0.5f;
;                 float* xb = XR + (size_t)(256 * u.pm + 64 * wr + fr) * 1024 + n;
; #pragma unroll
;                 for (int ai = 0; ai < 2; ++ai)
; #pragma unroll
;                     for (int mm = 0; mm < 4; ++mm) {
;                         float* xp = xb + (size_t)(128 * ai + 16 * mm) * 1024;
;                         const f32x4 v = acc[ai][bj][mm][nn] * gt;
; #pragma unroll
;                         for (int r = 0; r < 4; ++r) (void)__hip_atomic_fetch_add(xp + r, v[r], __ATOMIC_RELAXED, __HIP_MEMORY_SCOPE_AGENT);
;                     }
;                 asm volatile("" ::: "memory");
;             }
	v_mul_f32_e32 v163, 0.5, v163
	v_mul_f32_e32 v164, 0.5, v164
	v_mul_f32_e32 v165, 0.5, v165
	v_mul_f32_e32 v166, 0.5, v166
	s_mov_b32 vcc_lo, 0x55555555
	s_mov_b32 vcc_hi, 0x55555555
	v_cndmask_b32_e32 v172, v124, v125, vcc
	v_cndmask_b32_e32 v173, v126, v127, vcc
	s_nop 0
	v_cndmask_b32_dpp v124, v172, v124, vcc quad_perm:[1,0,3,2] row_mask:0xf bank_mask:0xf
	v_cndmask_b32_dpp v126, v173, v126, vcc quad_perm:[1,0,3,2] row_mask:0xf bank_mask:0xf
	s_mov_b32 vcc_lo, 0xaaaaaaaa
	s_mov_b32 vcc_hi, 0xaaaaaaaa
	v_cndmask_b32_dpp v125, v172, v125, vcc quad_perm:[1,0,3,2] row_mask:0xf bank_mask:0xf
	v_cndmask_b32_dpp v127, v173, v127, vcc quad_perm:[1,0,3,2] row_mask:0xf bank_mask:0xf
	s_mov_b32 vcc_lo, 0x33333333
	s_mov_b32 vcc_hi, 0x33333333
	v_cndmask_b32_e32 v172, v124, v126, vcc
	v_cndmask_b32_e32 v173, v125, v127, vcc
	s_nop 0
	v_cndmask_b32_dpp v124, v172, v124, vcc quad_perm:[2,3,0,1] row_mask:0xf bank_mask:0xf
	v_cndmask_b32_dpp v125, v173, v125, vcc quad_perm:[2,3,0,1] row_mask:0xf bank_mask:0xf
	s_mov_b32 vcc_lo, 0xcccccccc
	s_mov_b32 vcc_hi, 0xcccccccc
	v_cndmask_b32_dpp v126, v172, v126, vcc quad_perm:[2,3,0,1] row_mask:0xf bank_mask:0xf
	v_cndmask_b32_dpp v127, v173, v127, vcc quad_perm:[2,3,0,1] row_mask:0xf bank_mask:0xf
	v_mul_f32_e32 v124, v124, v163
	v_mul_f32_e32 v125, v125, v163
	v_mul_f32_e32 v126, v126, v163
	v_mul_f32_e32 v127, v127, v163
	global_atomic_add_f32 v[152:153], v124, off offset:-4096
	global_atomic_add_f32 v[152:153], v125, off
	v_lshl_add_u64 v[152:153], v[152:153], 0, s[98:99]
	global_atomic_add_f32 v[152:153], v126, off offset:-4096
	global_atomic_add_f32 v[152:153], v127, off
	s_mov_b32 vcc_lo, 0x55555555
	s_mov_b32 vcc_hi, 0x55555555
	v_cndmask_b32_e32 v172, v120, v121, vcc
	v_cndmask_b32_e32 v173, v122, v123, vcc
	s_nop 0
	v_cndmask_b32_dpp v120, v172, v120, vcc quad_perm:[1,0,3,2] row_mask:0xf bank_mask:0xf
	v_cndmask_b32_dpp v122, v173, v122, vcc quad_perm:[1,0,3,2] row_mask:0xf bank_mask:0xf
	s_mov_b32 vcc_lo, 0xaaaaaaaa
	s_mov_b32 vcc_hi, 0xaaaaaaaa
	v_cndmask_b32_dpp v121, v172, v121, vcc quad_perm:[1,0,3,2] row_mask:0xf bank_mask:0xf
	v_cndmask_b32_dpp v123, v173, v123, vcc quad_perm:[1,0,3,2] row_mask:0xf bank_mask:0xf
	s_mov_b32 vcc_lo, 0x33333333
	s_mov_b32 vcc_hi, 0x33333333
	v_cndmask_b32_e32 v172, v120, v122, vcc
	v_cndmask_b32_e32 v173, v121, v123, vcc
	s_nop 0
	v_cndmask_b32_dpp v120, v172, v120, vcc quad_perm:[2,3,0,1] row_mask:0xf bank_mask:0xf
	v_cndmask_b32_dpp v121, v173, v121, vcc quad_perm:[2,3,0,1] row_mask:0xf bank_mask:0xf
	s_mov_b32 vcc_lo, 0xcccccccc
	s_mov_b32 vcc_hi, 0xcccccccc
	v_cndmask_b32_dpp v122, v172, v122, vcc quad_perm:[2,3,0,1] row_mask:0xf bank_mask:0xf
	v_cndmask_b32_dpp v123, v173, v123, vcc quad_perm:[2,3,0,1] row_mask:0xf bank_mask:0xf
	v_mul_f32_e32 v120, v120, v163
	v_mul_f32_e32 v121, v121, v163
	v_mul_f32_e32 v122, v122, v163
	v_mul_f32_e32 v123, v123, v163
	global_atomic_add_f32 v[150:151], v120, off offset:-4096
	global_atomic_add_f32 v[150:151], v121, off
	v_lshl_add_u64 v[150:151], v[150:151], 0, s[98:99]
	global_atomic_add_f32 v[150:151], v122, off offset:-4096
	global_atomic_add_f32 v[150:151], v123, off
	s_mov_b32 vcc_lo, 0x55555555
	s_mov_b32 vcc_hi, 0x55555555
	v_cndmask_b32_e32 v172, v116, v117, vcc
	v_cndmask_b32_e32 v173, v118, v119, vcc
	s_nop 0
	v_cndmask_b32_dpp v116, v172, v116, vcc quad_perm:[1,0,3,2] row_mask:0xf bank_mask:0xf
	v_cndmask_b32_dpp v118, v173, v118, vcc quad_perm:[1,0,3,2] row_mask:0xf bank_mask:0xf
	s_mov_b32 vcc_lo, 0xaaaaaaaa
	s_mov_b32 vcc_hi, 0xaaaaaaaa
	v_cndmask_b32_dpp v117, v172, v117, vcc quad_perm:[1,0,3,2] row_mask:0xf bank_mask:0xf
	v_cndmask_b32_dpp v119, v173, v119, vcc quad_perm:[1,0,3,2] row_mask:0xf bank_mask:0xf
	s_mov_b32 vcc_lo, 0x33333333
	s_mov_b32 vcc_hi, 0x33333333
	v_cndmask_b32_e32 v172, v116, v118, vcc
	v_cndmask_b32_e32 v173, v117, v119, vcc
	s_nop 0
	v_cndmask_b32_dpp v116, v172, v116, vcc quad_perm:[2,3,0,1] row_mask:0xf bank_mask:0xf
	v_cndmask_b32_dpp v117, v173, v117, vcc quad_perm:[2,3,0,1] row_mask:0xf bank_mask:0xf
	s_mov_b32 vcc_lo, 0xcccccccc
	s_mov_b32 vcc_hi, 0xcccccccc
	v_cndmask_b32_dpp v118, v172, v118, vcc quad_perm:[2,3,0,1] row_mask:0xf bank_mask:0xf
	v_cndmask_b32_dpp v119, v173, v119, vcc quad_perm:[2,3,0,1] row_mask:0xf bank_mask:0xf
	v_mul_f32_e32 v116, v116, v163
	v_mul_f32_e32 v117, v117, v163
	v_mul_f32_e32 v118, v118, v163
	v_mul_f32_e32 v119, v119, v163
	global_atomic_add_f32 v[148:149], v116, off offset:-4096
	global_atomic_add_f32 v[148:149], v117, off
	v_lshl_add_u64 v[148:149], v[148:149], 0, s[98:99]
	global_atomic_add_f32 v[148:149], v118, off offset:-4096
	global_atomic_add_f32 v[148:149], v119, off
	s_mov_b32 vcc_lo, 0x55555555
	s_mov_b32 vcc_hi, 0x55555555
	v_cndmask_b32_e32 v172, v112, v113, vcc
	v_cndmask_b32_e32 v173, v114, v115, vcc
	s_nop 0
	v_cndmask_b32_dpp v112, v172, v112, vcc quad_perm:[1,0,3,2] row_mask:0xf bank_mask:0xf
	v_cndmask_b32_dpp v114, v173, v114, vcc quad_perm:[1,0,3,2] row_mask:0xf bank_mask:0xf
	s_mov_b32 vcc_lo, 0xaaaaaaaa
	s_mov_b32 vcc_hi, 0xaaaaaaaa
	v_cndmask_b32_dpp v113, v172, v113, vcc quad_perm:[1,0,3,2] row_mask:0xf bank_mask:0xf
	v_cndmask_b32_dpp v115, v173, v115, vcc quad_perm:[1,0,3,2] row_mask:0xf bank_mask:0xf
	s_mov_b32 vcc_lo, 0x33333333
	s_mov_b32 vcc_hi, 0x33333333
	v_cndmask_b32_e32 v172, v112, v114, vcc
	v_cndmask_b32_e32 v173, v113, v115, vcc
	s_nop 0
	v_cndmask_b32_dpp v112, v172, v112, vcc quad_perm:[2,3,0,1] row_mask:0xf bank_mask:0xf
	v_cndmask_b32_dpp v113, v173, v113, vcc quad_perm:[2,3,0,1] row_mask:0xf bank_mask:0xf
	s_mov_b32 vcc_lo, 0xcccccccc
	s_mov_b32 vcc_hi, 0xcccccccc
;     __device__ __forceinline__ void operator()(const AccT& acc, const Unit& u, int wr, int wc, int fr, int fq) const {
; #pragma unroll
;         for (int bj = 0; bj < 2; ++bj)
; #pragma unroll
;             for (int nn = 0; nn < 2; ++nn) {
;                 const int n = 256 * u.pn + 128 * bj + 32 * wc + 16 * nn + 4 * fq;
;                 const f32x4 gt = *(const f32x4*)(mod + 4 * 9216 + 2 * 1024 + n) * 0.5f;
;                 float* xb = XR + (size_t)(256 * u.pm + 64 * wr + fr) * 1024 + n;
; #pragma unroll
;                 for (int ai = 0; ai < 2; ++ai)
; #pragma unroll
;                     for (int mm = 0; mm < 4; ++mm) {
;                         float* xp = xb + (size_t)(128 * ai + 16 * mm) * 1024;
;                         const f32x4 v = acc[ai][bj][mm][nn] * gt;
; #pragma unroll
;                         for (int r = 0; r < 4; ++r) (void)__hip_atomic_fetch_add(xp + r, v[r], __ATOMIC_RELAXED, __HIP_MEMORY_SCOPE_AGENT);
;                     }
;                 asm volatile("" ::: "memory");
;             }
	v_cndmask_b32_dpp v114, v172, v114, vcc quad_perm:[2,3,0,1] row_mask:0xf bank_mask:0xf
	v_cndmask_b32_dpp v115, v173, v115, vcc quad_perm:[2,3,0,1] row_mask:0xf bank_mask:0xf
	v_mul_f32_e32 v112, v112, v163
	v_mul_f32_e32 v113, v113, v163
	v_mul_f32_e32 v114, v114, v163
	v_mul_f32_e32 v115, v115, v163
	global_atomic_add_f32 v[142:143], v112, off offset:-4096
	global_atomic_add_f32 v[142:143], v113, off
	v_lshl_add_u64 v[142:143], v[142:143], 0, s[98:99]
	global_atomic_add_f32 v[142:143], v114, off offset:-4096
	global_atomic_add_f32 v[142:143], v115, off
	s_mov_b32 vcc_lo, 0x55555555
	s_mov_b32 vcc_hi, 0x55555555
	v_cndmask_b32_e32 v172, v108, v109, vcc
	v_cndmask_b32_e32 v173, v110, v111, vcc
	s_nop 0
	v_cndmask_b32_dpp v108, v172, v108, vcc quad_perm:[1,0,3,2] row_mask:0xf bank_mask:0xf
	v_cndmask_b32_dpp v110, v173, v110, vcc quad_perm:[1,0,3,2] row_mask:0xf bank_mask:0xf
	s_mov_b32 vcc_lo, 0xaaaaaaaa
	s_mov_b32 vcc_hi, 0xaaaaaaaa
	v_cndmask_b32_dpp v109, v172, v109, vcc quad_perm:[1,0,3,2] row_mask:0xf bank_mask:0xf
	v_cndmask_b32_dpp v111, v173, v111, vcc quad_perm:[1,0,3,2] row_mask:0xf bank_mask:0xf
	s_mov_b32 vcc_lo, 0x33333333
	s_mov_b32 vcc_hi, 0x33333333
	v_cndmask_b32_e32 v172, v108, v110, vcc
	v_cndmask_b32_e32 v173, v109, v111, vcc
	s_nop 0
	v_cndmask_b32_dpp v108, v172, v108, vcc quad_perm:[2,3,0,1] row_mask:0xf bank_mask:0xf
	v_cndmask_b32_dpp v109, v173, v109, vcc quad_perm:[2,3,0,1] row_mask:0xf bank_mask:0xf
	s_mov_b32 vcc_lo, 0xcccccccc
	s_mov_b32 vcc_hi, 0xcccccccc
	v_cndmask_b32_dpp v110, v172, v110, vcc quad_perm:[2,3,0,1] row_mask:0xf bank_mask:0xf
	v_cndmask_b32_dpp v111, v173, v111, vcc quad_perm:[2,3,0,1] row_mask:0xf bank_mask:0xf
	v_mul_f32_e32 v108, v108, v163
	v_mul_f32_e32 v109, v109, v163
	v_mul_f32_e32 v110, v110, v163
	v_mul_f32_e32 v111, v111, v163
	global_atomic_add_f32 v[140:141], v108, off offset:-4096
	global_atomic_add_f32 v[140:141], v109, off
	v_lshl_add_u64 v[140:141], v[140:141], 0, s[98:99]
	global_atomic_add_f32 v[140:141], v110, off offset:-4096
	global_atomic_add_f32 v[140:141], v111, off
	s_mov_b32 vcc_lo, 0x55555555
	s_mov_b32 vcc_hi, 0x55555555
	v_cndmask_b32_e32 v172, v104, v105, vcc
	v_cndmask_b32_e32 v173, v106, v107, vcc
	s_nop 0
	v_cndmask_b32_dpp v104, v172, v104, vcc quad_perm:[1,0,3,2] row_mask:0xf bank_mask:0xf
	v_cndmask_b32_dpp v106, v173, v106, vcc quad_perm:[1,0,3,2] row_mask:0xf bank_mask:0xf
	s_mov_b32 vcc_lo, 0xaaaaaaaa
	s_mov_b32 vcc_hi, 0xaaaaaaaa
	v_cndmask_b32_dpp v105, v172, v105, vcc quad_perm:[1,0,3,2] row_mask:0xf bank_mask:0xf
	v_cndmask_b32_dpp v107, v173, v107, vcc quad_perm:[1,0,3,2] row_mask:0xf bank_mask:0xf
	s_mov_b32 vcc_lo, 0x33333333
	s_mov_b32 vcc_hi, 0x33333333
	v_cndmask_b32_e32 v172, v104, v106, vcc
	v_cndmask_b32_e32 v173, v105, v107, vcc
	s_nop 0
	v_cndmask_b32_dpp v104, v172, v104, vcc quad_perm:[2,3,0,1] row_mask:0xf bank_mask:0xf
	v_cndmask_b32_dpp v105, v173, v105, vcc quad_perm:[2,3,0,1] row_mask:0xf bank_mask:0xf
	s_mov_b32 vcc_lo, 0xcccccccc
	s_mov_b32 vcc_hi, 0xcccccccc
	v_cndmask_b32_dpp v106, v172, v106, vcc quad_perm:[2,3,0,1] row_mask:0xf bank_mask:0xf
	v_cndmask_b32_dpp v107, v173, v107, vcc quad_perm:[2,3,0,1] row_mask:0xf bank_mask:0xf
	v_mul_f32_e32 v104, v104, v163
	v_mul_f32_e32 v105, v105, v163
	v_mul_f32_e32 v106, v106, v163
	v_mul_f32_e32 v107, v107, v163
	global_atomic_add_f32 v[138:139], v104, off offset:-4096
	global_atomic_add_f32 v[138:139], v105, off
	v_lshl_add_u64 v[138:139], v[138:139], 0, s[98:99]
	global_atomic_add_f32 v[138:139], v106, off offset:-4096
	global_atomic_add_f32 v[138:139], v107, off
	s_mov_b32 vcc_lo, 0x55555555
	s_mov_b32 vcc_hi, 0x55555555
	v_cndmask_b32_e32 v172, v100, v101, vcc
	v_cndmask_b32_e32 v173, v102, v103, vcc
	s_nop 0
	v_cndmask_b32_dpp v100, v172, v100, vcc quad_perm:[1,0,3,2] row_mask:0xf bank_mask:0xf
	v_cndmask_b32_dpp v102, v173, v102, vcc quad_perm:[1,0,3,2] row_mask:0xf bank_mask:0xf
	s_mov_b32 vcc_lo, 0xaaaaaaaa
	s_mov_b32 vcc_hi, 0xaaaaaaaa
	v_cndmask_b32_dpp v101, v172, v101, vcc quad_perm:[1,0,3,2] row_mask:0xf bank_mask:0xf
	v_cndmask_b32_dpp v103, v173, v103, vcc quad_perm:[1,0,3,2] row_mask:0xf bank_mask:0xf
	s_mov_b32 vcc_lo, 0x33333333
	s_mov_b32 vcc_hi, 0x33333333
	v_cndmask_b32_e32 v172, v100, v102, vcc
	v_cndmask_b32_e32 v173, v101, v103, vcc
	s_nop 0
	v_cndmask_b32_dpp v100, v172, v100, vcc quad_perm:[2,3,0,1] row_mask:0xf bank_mask:0xf
	v_cndmask_b32_dpp v101, v173, v101, vcc quad_perm:[2,3,0,1] row_mask:0xf bank_mask:0xf
	s_mov_b32 vcc_lo, 0xcccccccc
	s_mov_b32 vcc_hi, 0xcccccccc
	v_cndmask_b32_dpp v102, v172, v102, vcc quad_perm:[2,3,0,1] row_mask:0xf bank_mask:0xf
	v_cndmask_b32_dpp v103, v173, v103, vcc quad_perm:[2,3,0,1] row_mask:0xf bank_mask:0xf
	v_mul_f32_e32 v100, v100, v163
	v_mul_f32_e32 v101, v101, v163
	v_mul_f32_e32 v102, v102, v163
	v_mul_f32_e32 v103, v103, v163
	global_atomic_add_f32 v[136:137], v100, off offset:-4096
	global_atomic_add_f32 v[136:137], v101, off
	v_lshl_add_u64 v[136:137], v[136:137], 0, s[98:99]
	global_atomic_add_f32 v[136:137], v102, off offset:-4096
	global_atomic_add_f32 v[136:137], v103, off
	s_mov_b32 vcc_lo, 0x55555555
	s_mov_b32 vcc_hi, 0x55555555
	v_cndmask_b32_e32 v172, v96, v97, vcc
	v_cndmask_b32_e32 v173, v98, v99, vcc
	s_nop 0
	v_cndmask_b32_dpp v96, v172, v96, vcc quad_perm:[1,0,3,2] row_mask:0xf bank_mask:0xf
	v_cndmask_b32_dpp v98, v173, v98, vcc quad_perm:[1,0,3,2] row_mask:0xf bank_mask:0xf
	s_mov_b32 vcc_lo, 0xaaaaaaaa
	s_mov_b32 vcc_hi, 0xaaaaaaaa
	v_cndmask_b32_dpp v97, v172, v97, vcc quad_perm:[1,0,3,2] row_mask:0xf bank_mask:0xf
	v_cndmask_b32_dpp v99, v173, v99, vcc quad_perm:[1,0,3,2] row_mask:0xf bank_mask:0xf
;     __device__ __forceinline__ void operator()(const AccT& acc, const Unit& u, int wr, int wc, int fr, int fq) const {
; #pragma unroll
;         for (int bj = 0; bj < 2; ++bj)
; #pragma unroll
;             for (int nn = 0; nn < 2; ++nn) {
;                 const int n = 256 * u.pn + 128 * bj + 32 * wc + 16 * nn + 4 * fq;
;                 const f32x4 gt = *(const f32x4*)(mod + 4 * 9216 + 2 * 1024 + n) * 0.5f;
;                 float* xb = XR + (size_t)(256 * u.pm + 64 * wr + fr) * 1024 + n;
; #pragma unroll
;                 for (int ai = 0; ai < 2; ++ai)
; #pragma unroll
;                     for (int mm = 0; mm < 4; ++mm) {
;                         float* xp = xb + (size_t)(128 * ai + 16 * mm) * 1024;
;                         const f32x4 v = acc[ai][bj][mm][nn] * gt;
; #pragma unroll
;                         for (int r = 0; r < 4; ++r) (void)__hip_atomic_fetch_add(xp + r, v[r], __ATOMIC_RELAXED, __HIP_MEMORY_SCOPE_AGENT);
;                     }
;                 asm volatile("" ::: "memory");
;             }
	s_mov_b32 vcc_lo, 0x33333333
	s_mov_b32 vcc_hi, 0x33333333
	v_cndmask_b32_e32 v172, v96, v98, vcc
	v_cndmask_b32_e32 v173, v97, v99, vcc
	s_nop 0
	v_cndmask_b32_dpp v96, v172, v96, vcc quad_perm:[2,3,0,1] row_mask:0xf bank_mask:0xf
	v_cndmask_b32_dpp v97, v173, v97, vcc quad_perm:[2,3,0,1] row_mask:0xf bank_mask:0xf
	s_mov_b32 vcc_lo, 0xcccccccc
	s_mov_b32 vcc_hi, 0xcccccccc
	v_cndmask_b32_dpp v98, v172, v98, vcc quad_perm:[2,3,0,1] row_mask:0xf bank_mask:0xf
	v_cndmask_b32_dpp v99, v173, v99, vcc quad_perm:[2,3,0,1] row_mask:0xf bank_mask:0xf
	v_mul_f32_e32 v96, v96, v163
	v_mul_f32_e32 v97, v97, v163
	v_mul_f32_e32 v98, v98, v163
	v_mul_f32_e32 v99, v99, v163
	global_atomic_add_f32 v[134:135], v96, off offset:-4096
	global_atomic_add_f32 v[134:135], v97, off
	v_lshl_add_u64 v[134:135], v[134:135], 0, s[98:99]
	global_atomic_add_f32 v[134:135], v98, off offset:-4096
	global_atomic_add_f32 v[134:135], v99, off
	s_mov_b32 vcc_lo, 0x55555555
	s_mov_b32 vcc_hi, 0x55555555
	v_cndmask_b32_e32 v172, v92, v93, vcc
	v_cndmask_b32_e32 v173, v94, v95, vcc
	s_nop 0
	v_cndmask_b32_dpp v92, v172, v92, vcc quad_perm:[1,0,3,2] row_mask:0xf bank_mask:0xf
	v_cndmask_b32_dpp v94, v173, v94, vcc quad_perm:[1,0,3,2] row_mask:0xf bank_mask:0xf
	s_mov_b32 vcc_lo, 0xaaaaaaaa
	s_mov_b32 vcc_hi, 0xaaaaaaaa
	v_cndmask_b32_dpp v93, v172, v93, vcc quad_perm:[1,0,3,2] row_mask:0xf bank_mask:0xf
	v_cndmask_b32_dpp v95, v173, v95, vcc quad_perm:[1,0,3,2] row_mask:0xf bank_mask:0xf
	s_mov_b32 vcc_lo, 0x33333333
	s_mov_b32 vcc_hi, 0x33333333
	v_cndmask_b32_e32 v172, v92, v94, vcc
	v_cndmask_b32_e32 v173, v93, v95, vcc
	s_nop 0
	v_cndmask_b32_dpp v92, v172, v92, vcc quad_perm:[2,3,0,1] row_mask:0xf bank_mask:0xf
	v_cndmask_b32_dpp v93, v173, v93, vcc quad_perm:[2,3,0,1] row_mask:0xf bank_mask:0xf
	s_mov_b32 vcc_lo, 0xcccccccc
	s_mov_b32 vcc_hi, 0xcccccccc
	v_cndmask_b32_dpp v94, v172, v94, vcc quad_perm:[2,3,0,1] row_mask:0xf bank_mask:0xf
	v_cndmask_b32_dpp v95, v173, v95, vcc quad_perm:[2,3,0,1] row_mask:0xf bank_mask:0xf
	v_mul_f32_e32 v92, v92, v164
	v_mul_f32_e32 v93, v93, v164
	v_mul_f32_e32 v94, v94, v164
	v_mul_f32_e32 v95, v95, v164
	global_atomic_add_f32 v[152:153], v94, off offset:-4032
	global_atomic_add_f32 v[152:153], v95, off offset:64
	v_lshl_add_u64 v[152:153], v[152:153], 0, s[100:101]
	global_atomic_add_f32 v[152:153], v92, off offset:-4032
	global_atomic_add_f32 v[152:153], v93, off offset:64
	s_mov_b32 vcc_lo, 0x55555555
	s_mov_b32 vcc_hi, 0x55555555
	v_cndmask_b32_e32 v172, v88, v89, vcc
	v_cndmask_b32_e32 v173, v90, v91, vcc
	s_nop 0
	v_cndmask_b32_dpp v88, v172, v88, vcc quad_perm:[1,0,3,2] row_mask:0xf bank_mask:0xf
	v_cndmask_b32_dpp v90, v173, v90, vcc quad_perm:[1,0,3,2] row_mask:0xf bank_mask:0xf
	s_mov_b32 vcc_lo, 0xaaaaaaaa
	s_mov_b32 vcc_hi, 0xaaaaaaaa
	v_cndmask_b32_dpp v89, v172, v89, vcc quad_perm:[1,0,3,2] row_mask:0xf bank_mask:0xf
	v_cndmask_b32_dpp v91, v173, v91, vcc quad_perm:[1,0,3,2] row_mask:0xf bank_mask:0xf
	s_mov_b32 vcc_lo, 0x33333333
	s_mov_b32 vcc_hi, 0x33333333
	v_cndmask_b32_e32 v172, v88, v90, vcc
	v_cndmask_b32_e32 v173, v89, v91, vcc
	s_nop 0
	v_cndmask_b32_dpp v88, v172, v88, vcc quad_perm:[2,3,0,1] row_mask:0xf bank_mask:0xf
	v_cndmask_b32_dpp v89, v173, v89, vcc quad_perm:[2,3,0,1] row_mask:0xf bank_mask:0xf
	s_mov_b32 vcc_lo, 0xcccccccc
	s_mov_b32 vcc_hi, 0xcccccccc
	v_cndmask_b32_dpp v90, v172, v90, vcc quad_perm:[2,3,0,1] row_mask:0xf bank_mask:0xf
	v_cndmask_b32_dpp v91, v173, v91, vcc quad_perm:[2,3,0,1] row_mask:0xf bank_mask:0xf
	v_mul_f32_e32 v88, v88, v164
	v_mul_f32_e32 v89, v89, v164
	v_mul_f32_e32 v90, v90, v164
	v_mul_f32_e32 v91, v91, v164
	global_atomic_add_f32 v[150:151], v90, off offset:-4032
	global_atomic_add_f32 v[150:151], v91, off offset:64
	v_lshl_add_u64 v[150:151], v[150:151], 0, s[100:101]
	global_atomic_add_f32 v[150:151], v88, off offset:-4032
	global_atomic_add_f32 v[150:151], v89, off offset:64
	s_mov_b32 vcc_lo, 0x55555555
	s_mov_b32 vcc_hi, 0x55555555
	v_cndmask_b32_e32 v172, v84, v85, vcc
	v_cndmask_b32_e32 v173, v86, v87, vcc
	s_nop 0
	v_cndmask_b32_dpp v84, v172, v84, vcc quad_perm:[1,0,3,2] row_mask:0xf bank_mask:0xf
	v_cndmask_b32_dpp v86, v173, v86, vcc quad_perm:[1,0,3,2] row_mask:0xf bank_mask:0xf
	s_mov_b32 vcc_lo, 0xaaaaaaaa
	s_mov_b32 vcc_hi, 0xaaaaaaaa
	v_cndmask_b32_dpp v85, v172, v85, vcc quad_perm:[1,0,3,2] row_mask:0xf bank_mask:0xf
	v_cndmask_b32_dpp v87, v173, v87, vcc quad_perm:[1,0,3,2] row_mask:0xf bank_mask:0xf
	s_mov_b32 vcc_lo, 0x33333333
	s_mov_b32 vcc_hi, 0x33333333
	v_cndmask_b32_e32 v172, v84, v86, vcc
	v_cndmask_b32_e32 v173, v85, v87, vcc
	s_nop 0
	v_cndmask_b32_dpp v84, v172, v84, vcc quad_perm:[2,3,0,1] row_mask:0xf bank_mask:0xf
	v_cndmask_b32_dpp v85, v173, v85, vcc quad_perm:[2,3,0,1] row_mask:0xf bank_mask:0xf
	s_mov_b32 vcc_lo, 0xcccccccc
	s_mov_b32 vcc_hi, 0xcccccccc
	v_cndmask_b32_dpp v86, v172, v86, vcc quad_perm:[2,3,0,1] row_mask:0xf bank_mask:0xf
	v_cndmask_b32_dpp v87, v173, v87, vcc quad_perm:[2,3,0,1] row_mask:0xf bank_mask:0xf
	v_mul_f32_e32 v84, v84, v164
	v_mul_f32_e32 v85, v85, v164
	v_mul_f32_e32 v86, v86, v164
	v_mul_f32_e32 v87, v87, v164
	global_atomic_add_f32 v[148:149], v86, off offset:-4032
	global_atomic_add_f32 v[148:149], v87, off offset:64
	v_lshl_add_u64 v[148:149], v[148:149], 0, s[100:101]
	global_atomic_add_f32 v[148:149], v84, off offset:-4032
	global_atomic_add_f32 v[148:149], v85, off offset:64
	s_mov_b32 vcc_lo, 0x55555555
	s_mov_b32 vcc_hi, 0x55555555
	v_cndmask_b32_e32 v172, v80, v81, vcc
	v_cndmask_b32_e32 v173, v82, v83, vcc
	s_nop 0
	v_cndmask_b32_dpp v80, v172, v80, vcc quad_perm:[1,0,3,2] row_mask:0xf bank_mask:0xf
;     __device__ __forceinline__ void operator()(const AccT& acc, const Unit& u, int wr, int wc, int fr, int fq) const {
; #pragma unroll
;         for (int bj = 0; bj < 2; ++bj)
; #pragma unroll
;             for (int nn = 0; nn < 2; ++nn) {
;                 const int n = 256 * u.pn + 128 * bj + 32 * wc + 16 * nn + 4 * fq;
;                 const f32x4 gt = *(const f32x4*)(mod + 4 * 9216 + 2 * 1024 + n) * 0.5f;
;                 float* xb = XR + (size_t)(256 * u.pm + 64 * wr + fr) * 1024 + n;
; #pragma unroll
;                 for (int ai = 0; ai < 2; ++ai)
; #pragma unroll
;                     for (int mm = 0; mm < 4; ++mm) {
;                         float* xp = xb + (size_t)(128 * ai + 16 * mm) * 1024;
;                         const f32x4 v = acc[ai][bj][mm][nn] * gt;
; #pragma unroll
;                         for (int r = 0; r < 4; ++r) (void)__hip_atomic_fetch_add(xp + r, v[r], __ATOMIC_RELAXED, __HIP_MEMORY_SCOPE_AGENT);
;                     }
;                 asm volatile("" ::: "memory");
;             }
	v_cndmask_b32_dpp v82, v173, v82, vcc quad_perm:[1,0,3,2] row_mask:0xf bank_mask:0xf
	s_mov_b32 vcc_lo, 0xaaaaaaaa
	s_mov_b32 vcc_hi, 0xaaaaaaaa
	v_cndmask_b32_dpp v81, v172, v81, vcc quad_perm:[1,0,3,2] row_mask:0xf bank_mask:0xf
	v_cndmask_b32_dpp v83, v173, v83, vcc quad_perm:[1,0,3,2] row_mask:0xf bank_mask:0xf
	s_mov_b32 vcc_lo, 0x33333333
	s_mov_b32 vcc_hi, 0x33333333
	v_cndmask_b32_e32 v172, v80, v82, vcc
	v_cndmask_b32_e32 v173, v81, v83, vcc
	s_nop 0
	v_cndmask_b32_dpp v80, v172, v80, vcc quad_perm:[2,3,0,1] row_mask:0xf bank_mask:0xf
	v_cndmask_b32_dpp v81, v173, v81, vcc quad_perm:[2,3,0,1] row_mask:0xf bank_mask:0xf
	s_mov_b32 vcc_lo, 0xcccccccc
	s_mov_b32 vcc_hi, 0xcccccccc
	v_cndmask_b32_dpp v82, v172, v82, vcc quad_perm:[2,3,0,1] row_mask:0xf bank_mask:0xf
	v_cndmask_b32_dpp v83, v173, v83, vcc quad_perm:[2,3,0,1] row_mask:0xf bank_mask:0xf
	v_mul_f32_e32 v80, v80, v164
	v_mul_f32_e32 v81, v81, v164
	v_mul_f32_e32 v82, v82, v164
	v_mul_f32_e32 v83, v83, v164
	global_atomic_add_f32 v[142:143], v82, off offset:-4032
	global_atomic_add_f32 v[142:143], v83, off offset:64
	v_lshl_add_u64 v[142:143], v[142:143], 0, s[100:101]
	global_atomic_add_f32 v[142:143], v80, off offset:-4032
	global_atomic_add_f32 v[142:143], v81, off offset:64
	s_mov_b32 vcc_lo, 0x55555555
	s_mov_b32 vcc_hi, 0x55555555
	v_cndmask_b32_e32 v172, v76, v77, vcc
	v_cndmask_b32_e32 v173, v78, v79, vcc
	s_nop 0
	v_cndmask_b32_dpp v76, v172, v76, vcc quad_perm:[1,0,3,2] row_mask:0xf bank_mask:0xf
	v_cndmask_b32_dpp v78, v173, v78, vcc quad_perm:[1,0,3,2] row_mask:0xf bank_mask:0xf
	s_mov_b32 vcc_lo, 0xaaaaaaaa
	s_mov_b32 vcc_hi, 0xaaaaaaaa
	v_cndmask_b32_dpp v77, v172, v77, vcc quad_perm:[1,0,3,2] row_mask:0xf bank_mask:0xf
	v_cndmask_b32_dpp v79, v173, v79, vcc quad_perm:[1,0,3,2] row_mask:0xf bank_mask:0xf
	s_mov_b32 vcc_lo, 0x33333333
	s_mov_b32 vcc_hi, 0x33333333
	v_cndmask_b32_e32 v172, v76, v78, vcc
	v_cndmask_b32_e32 v173, v77, v79, vcc
	s_nop 0
	v_cndmask_b32_dpp v76, v172, v76, vcc quad_perm:[2,3,0,1] row_mask:0xf bank_mask:0xf
	v_cndmask_b32_dpp v77, v173, v77, vcc quad_perm:[2,3,0,1] row_mask:0xf bank_mask:0xf
	s_mov_b32 vcc_lo, 0xcccccccc
	s_mov_b32 vcc_hi, 0xcccccccc
	v_cndmask_b32_dpp v78, v172, v78, vcc quad_perm:[2,3,0,1] row_mask:0xf bank_mask:0xf
	v_cndmask_b32_dpp v79, v173, v79, vcc quad_perm:[2,3,0,1] row_mask:0xf bank_mask:0xf
	v_mul_f32_e32 v76, v76, v164
	v_mul_f32_e32 v77, v77, v164
	v_mul_f32_e32 v78, v78, v164
	v_mul_f32_e32 v79, v79, v164
	global_atomic_add_f32 v[140:141], v78, off offset:-4032
	global_atomic_add_f32 v[140:141], v79, off offset:64
	v_lshl_add_u64 v[140:141], v[140:141], 0, s[100:101]
	global_atomic_add_f32 v[140:141], v76, off offset:-4032
	global_atomic_add_f32 v[140:141], v77, off offset:64
	s_mov_b32 vcc_lo, 0x55555555
	s_mov_b32 vcc_hi, 0x55555555
	v_cndmask_b32_e32 v172, v72, v73, vcc
	v_cndmask_b32_e32 v173, v74, v75, vcc
	s_nop 0
	v_cndmask_b32_dpp v72, v172, v72, vcc quad_perm:[1,0,3,2] row_mask:0xf bank_mask:0xf
	v_cndmask_b32_dpp v74, v173, v74, vcc quad_perm:[1,0,3,2] row_mask:0xf bank_mask:0xf
	s_mov_b32 vcc_lo, 0xaaaaaaaa
	s_mov_b32 vcc_hi, 0xaaaaaaaa
	v_cndmask_b32_dpp v73, v172, v73, vcc quad_perm:[1,0,3,2] row_mask:0xf bank_mask:0xf
	v_cndmask_b32_dpp v75, v173, v75, vcc quad_perm:[1,0,3,2] row_mask:0xf bank_mask:0xf
	s_mov_b32 vcc_lo, 0x33333333
	s_mov_b32 vcc_hi, 0x33333333
	v_cndmask_b32_e32 v172, v72, v74, vcc
	v_cndmask_b32_e32 v173, v73, v75, vcc
	s_nop 0
	v_cndmask_b32_dpp v72, v172, v72, vcc quad_perm:[2,3,0,1] row_mask:0xf bank_mask:0xf
	v_cndmask_b32_dpp v73, v173, v73, vcc quad_perm:[2,3,0,1] row_mask:0xf bank_mask:0xf
	s_mov_b32 vcc_lo, 0xcccccccc
	s_mov_b32 vcc_hi, 0xcccccccc
	v_cndmask_b32_dpp v74, v172, v74, vcc quad_perm:[2,3,0,1] row_mask:0xf bank_mask:0xf
	v_cndmask_b32_dpp v75, v173, v75, vcc quad_perm:[2,3,0,1] row_mask:0xf bank_mask:0xf
	v_mul_f32_e32 v72, v72, v164
	v_mul_f32_e32 v73, v73, v164
	v_mul_f32_e32 v74, v74, v164
	v_mul_f32_e32 v75, v75, v164
	global_atomic_add_f32 v[138:139], v74, off offset:-4032
	global_atomic_add_f32 v[138:139], v75, off offset:64
	v_lshl_add_u64 v[138:139], v[138:139], 0, s[100:101]
	global_atomic_add_f32 v[138:139], v72, off offset:-4032
	global_atomic_add_f32 v[138:139], v73, off offset:64
	s_mov_b32 vcc_lo, 0x55555555
	s_mov_b32 vcc_hi, 0x55555555
	v_cndmask_b32_e32 v172, v68, v69, vcc
	v_cndmask_b32_e32 v173, v70, v71, vcc
	s_nop 0
	v_cndmask_b32_dpp v68, v172, v68, vcc quad_perm:[1,0,3,2] row_mask:0xf bank_mask:0xf
	v_cndmask_b32_dpp v70, v173, v70, vcc quad_perm:[1,0,3,2] row_mask:0xf bank_mask:0xf
	s_mov_b32 vcc_lo, 0xaaaaaaaa
	s_mov_b32 vcc_hi, 0xaaaaaaaa
	v_cndmask_b32_dpp v69, v172, v69, vcc quad_perm:[1,0,3,2] row_mask:0xf bank_mask:0xf
	v_cndmask_b32_dpp v71, v173, v71, vcc quad_perm:[1,0,3,2] row_mask:0xf bank_mask:0xf
	s_mov_b32 vcc_lo, 0x33333333
	s_mov_b32 vcc_hi, 0x33333333
	v_cndmask_b32_e32 v172, v68, v70, vcc
	v_cndmask_b32_e32 v173, v69, v71, vcc
	s_nop 0
	v_cndmask_b32_dpp v68, v172, v68, vcc quad_perm:[2,3,0,1] row_mask:0xf bank_mask:0xf
	v_cndmask_b32_dpp v69, v173, v69, vcc quad_perm:[2,3,0,1] row_mask:0xf bank_mask:0xf
	s_mov_b32 vcc_lo, 0xcccccccc
	s_mov_b32 vcc_hi, 0xcccccccc
	v_cndmask_b32_dpp v70, v172, v70, vcc quad_perm:[2,3,0,1] row_mask:0xf bank_mask:0xf
	v_cndmask_b32_dpp v71, v173, v71, vcc quad_perm:[2,3,0,1] row_mask:0xf bank_mask:0xf
	v_mul_f32_e32 v68, v68, v164
	v_mul_f32_e32 v69, v69, v164
	v_mul_f32_e32 v70, v70, v164
	v_mul_f32_e32 v71, v71, v164
	global_atomic_add_f32 v[136:137], v70, off offset:-4032
	global_atomic_add_f32 v[136:137], v71, off offset:64
	v_lshl_add_u64 v[136:137], v[136:137], 0, s[100:101]
;     __device__ __forceinline__ void operator()(const AccT& acc, const Unit& u, int wr, int wc, int fr, int fq) const {
; #pragma unroll
;         for (int bj = 0; bj < 2; ++bj)
; #pragma unroll
;             for (int nn = 0; nn < 2; ++nn) {
;                 const int n = 256 * u.pn + 128 * bj + 32 * wc + 16 * nn + 4 * fq;
;                 const f32x4 gt = *(const f32x4*)(mod + 4 * 9216 + 2 * 1024 + n) * 0.5f;
;                 float* xb = XR + (size_t)(256 * u.pm + 64 * wr + fr) * 1024 + n;
; #pragma unroll
;                 for (int ai = 0; ai < 2; ++ai)
; #pragma unroll
;                     for (int mm = 0; mm < 4; ++mm) {
;                         float* xp = xb + (size_t)(128 * ai + 16 * mm) * 1024;
;                         const f32x4 v = acc[ai][bj][mm][nn] * gt;
; #pragma unroll
;                         for (int r = 0; r < 4; ++r) (void)__hip_atomic_fetch_add(xp + r, v[r], __ATOMIC_RELAXED, __HIP_MEMORY_SCOPE_AGENT);
;                     }
;                 asm volatile("" ::: "memory");
;             }
	global_atomic_add_f32 v[136:137], v68, off offset:-4032
	global_atomic_add_f32 v[136:137], v69, off offset:64
	s_mov_b32 vcc_lo, 0x55555555
	s_mov_b32 vcc_hi, 0x55555555
	v_cndmask_b32_e32 v172, v64, v65, vcc
	v_cndmask_b32_e32 v173, v66, v67, vcc
	s_nop 0
	v_cndmask_b32_dpp v64, v172, v64, vcc quad_perm:[1,0,3,2] row_mask:0xf bank_mask:0xf
	v_cndmask_b32_dpp v66, v173, v66, vcc quad_perm:[1,0,3,2] row_mask:0xf bank_mask:0xf
	s_mov_b32 vcc_lo, 0xaaaaaaaa
	s_mov_b32 vcc_hi, 0xaaaaaaaa
	v_cndmask_b32_dpp v65, v172, v65, vcc quad_perm:[1,0,3,2] row_mask:0xf bank_mask:0xf
	v_cndmask_b32_dpp v67, v173, v67, vcc quad_perm:[1,0,3,2] row_mask:0xf bank_mask:0xf
	s_mov_b32 vcc_lo, 0x33333333
	s_mov_b32 vcc_hi, 0x33333333
	v_cndmask_b32_e32 v172, v64, v66, vcc
	v_cndmask_b32_e32 v173, v65, v67, vcc
	s_nop 0
	v_cndmask_b32_dpp v64, v172, v64, vcc quad_perm:[2,3,0,1] row_mask:0xf bank_mask:0xf
	v_cndmask_b32_dpp v65, v173, v65, vcc quad_perm:[2,3,0,1] row_mask:0xf bank_mask:0xf
	s_mov_b32 vcc_lo, 0xcccccccc
	s_mov_b32 vcc_hi, 0xcccccccc
	v_cndmask_b32_dpp v66, v172, v66, vcc quad_perm:[2,3,0,1] row_mask:0xf bank_mask:0xf
	v_cndmask_b32_dpp v67, v173, v67, vcc quad_perm:[2,3,0,1] row_mask:0xf bank_mask:0xf
	v_mul_f32_e32 v64, v64, v164
	v_mul_f32_e32 v65, v65, v164
	v_mul_f32_e32 v66, v66, v164
	v_mul_f32_e32 v67, v67, v164
	global_atomic_add_f32 v[134:135], v66, off offset:-4032
	global_atomic_add_f32 v[134:135], v67, off offset:64
	v_lshl_add_u64 v[134:135], v[134:135], 0, s[100:101]
	global_atomic_add_f32 v[134:135], v64, off offset:-4032
	global_atomic_add_f32 v[134:135], v65, off offset:64
	s_mov_b32 vcc_lo, 0x55555555
	s_mov_b32 vcc_hi, 0x55555555
	v_cndmask_b32_e32 v172, v60, v61, vcc
	v_cndmask_b32_e32 v173, v62, v63, vcc
	s_nop 0
	v_cndmask_b32_dpp v60, v172, v60, vcc quad_perm:[1,0,3,2] row_mask:0xf bank_mask:0xf
	v_cndmask_b32_dpp v62, v173, v62, vcc quad_perm:[1,0,3,2] row_mask:0xf bank_mask:0xf
	s_mov_b32 vcc_lo, 0xaaaaaaaa
	s_mov_b32 vcc_hi, 0xaaaaaaaa
	v_cndmask_b32_dpp v61, v172, v61, vcc quad_perm:[1,0,3,2] row_mask:0xf bank_mask:0xf
	v_cndmask_b32_dpp v63, v173, v63, vcc quad_perm:[1,0,3,2] row_mask:0xf bank_mask:0xf
	s_mov_b32 vcc_lo, 0x33333333
	s_mov_b32 vcc_hi, 0x33333333
	v_cndmask_b32_e32 v172, v60, v62, vcc
	v_cndmask_b32_e32 v173, v61, v63, vcc
	s_nop 0
	v_cndmask_b32_dpp v60, v172, v60, vcc quad_perm:[2,3,0,1] row_mask:0xf bank_mask:0xf
	v_cndmask_b32_dpp v61, v173, v61, vcc quad_perm:[2,3,0,1] row_mask:0xf bank_mask:0xf
	s_mov_b32 vcc_lo, 0xcccccccc
	s_mov_b32 vcc_hi, 0xcccccccc
	v_cndmask_b32_dpp v62, v172, v62, vcc quad_perm:[2,3,0,1] row_mask:0xf bank_mask:0xf
	v_cndmask_b32_dpp v63, v173, v63, vcc quad_perm:[2,3,0,1] row_mask:0xf bank_mask:0xf
	v_mul_f32_e32 v60, v60, v165
	v_mul_f32_e32 v61, v61, v165
	v_mul_f32_e32 v62, v62, v165
	v_mul_f32_e32 v63, v63, v165
	global_atomic_add_f32 v[152:153], v60, off offset:-3584
	global_atomic_add_f32 v[152:153], v61, off offset:512
	v_lshl_add_u64 v[152:153], v[152:153], 0, s[98:99]
	global_atomic_add_f32 v[152:153], v62, off offset:-3584
	global_atomic_add_f32 v[152:153], v63, off offset:512
	s_mov_b32 vcc_lo, 0x55555555
	s_mov_b32 vcc_hi, 0x55555555
	v_cndmask_b32_e32 v172, v56, v57, vcc
	v_cndmask_b32_e32 v173, v58, v59, vcc
	s_nop 0
	v_cndmask_b32_dpp v56, v172, v56, vcc quad_perm:[1,0,3,2] row_mask:0xf bank_mask:0xf
	v_cndmask_b32_dpp v58, v173, v58, vcc quad_perm:[1,0,3,2] row_mask:0xf bank_mask:0xf
	s_mov_b32 vcc_lo, 0xaaaaaaaa
	s_mov_b32 vcc_hi, 0xaaaaaaaa
	v_cndmask_b32_dpp v57, v172, v57, vcc quad_perm:[1,0,3,2] row_mask:0xf bank_mask:0xf
	v_cndmask_b32_dpp v59, v173, v59, vcc quad_perm:[1,0,3,2] row_mask:0xf bank_mask:0xf
	s_mov_b32 vcc_lo, 0x33333333
	s_mov_b32 vcc_hi, 0x33333333
	v_cndmask_b32_e32 v172, v56, v58, vcc
	v_cndmask_b32_e32 v173, v57, v59, vcc
	s_nop 0
	v_cndmask_b32_dpp v56, v172, v56, vcc quad_perm:[2,3,0,1] row_mask:0xf bank_mask:0xf
	v_cndmask_b32_dpp v57, v173, v57, vcc quad_perm:[2,3,0,1] row_mask:0xf bank_mask:0xf
	s_mov_b32 vcc_lo, 0xcccccccc
	s_mov_b32 vcc_hi, 0xcccccccc
	v_cndmask_b32_dpp v58, v172, v58, vcc quad_perm:[2,3,0,1] row_mask:0xf bank_mask:0xf
	v_cndmask_b32_dpp v59, v173, v59, vcc quad_perm:[2,3,0,1] row_mask:0xf bank_mask:0xf
	v_mul_f32_e32 v56, v56, v165
	v_mul_f32_e32 v57, v57, v165
	v_mul_f32_e32 v58, v58, v165
	v_mul_f32_e32 v59, v59, v165
	global_atomic_add_f32 v[150:151], v56, off offset:-3584
	global_atomic_add_f32 v[150:151], v57, off offset:512
	v_lshl_add_u64 v[150:151], v[150:151], 0, s[98:99]
	global_atomic_add_f32 v[150:151], v58, off offset:-3584
	global_atomic_add_f32 v[150:151], v59, off offset:512
	s_mov_b32 vcc_lo, 0x55555555
	s_mov_b32 vcc_hi, 0x55555555
	v_cndmask_b32_e32 v172, v52, v53, vcc
	v_cndmask_b32_e32 v173, v54, v55, vcc
	s_nop 0
	v_cndmask_b32_dpp v52, v172, v52, vcc quad_perm:[1,0,3,2] row_mask:0xf bank_mask:0xf
	v_cndmask_b32_dpp v54, v173, v54, vcc quad_perm:[1,0,3,2] row_mask:0xf bank_mask:0xf
	s_mov_b32 vcc_lo, 0xaaaaaaaa
	s_mov_b32 vcc_hi, 0xaaaaaaaa
	v_cndmask_b32_dpp v53, v172, v53, vcc quad_perm:[1,0,3,2] row_mask:0xf bank_mask:0xf
	v_cndmask_b32_dpp v55, v173, v55, vcc quad_perm:[1,0,3,2] row_mask:0xf bank_mask:0xf
	s_mov_b32 vcc_lo, 0x33333333
	s_mov_b32 vcc_hi, 0x33333333
	v_cndmask_b32_e32 v172, v52, v54, vcc
	v_cndmask_b32_e32 v173, v53, v55, vcc
	s_nop 0
	v_cndmask_b32_dpp v52, v172, v52, vcc quad_perm:[2,3,0,1] row_mask:0xf bank_mask:0xf
	v_cndmask_b32_dpp v53, v173, v53, vcc quad_perm:[2,3,0,1] row_mask:0xf bank_mask:0xf
	s_mov_b32 vcc_lo, 0xcccccccc
	s_mov_b32 vcc_hi, 0xcccccccc
	v_cndmask_b32_dpp v54, v172, v54, vcc quad_perm:[2,3,0,1] row_mask:0xf bank_mask:0xf
;     __device__ __forceinline__ void operator()(const AccT& acc, const Unit& u, int wr, int wc, int fr, int fq) const {
; #pragma unroll
;         for (int bj = 0; bj < 2; ++bj)
; #pragma unroll
;             for (int nn = 0; nn < 2; ++nn) {
;                 const int n = 256 * u.pn + 128 * bj + 32 * wc + 16 * nn + 4 * fq;
;                 const f32x4 gt = *(const f32x4*)(mod + 4 * 9216 + 2 * 1024 + n) * 0.5f;
;                 float* xb = XR + (size_t)(256 * u.pm + 64 * wr + fr) * 1024 + n;
; #pragma unroll
;                 for (int ai = 0; ai < 2; ++ai)
; #pragma unroll
;                     for (int mm = 0; mm < 4; ++mm) {
;                         float* xp = xb + (size_t)(128 * ai + 16 * mm) * 1024;
;                         const f32x4 v = acc[ai][bj][mm][nn] * gt;
; #pragma unroll
;                         for (int r = 0; r < 4; ++r) (void)__hip_atomic_fetch_add(xp + r, v[r], __ATOMIC_RELAXED, __HIP_MEMORY_SCOPE_AGENT);
;                     }
;                 asm volatile("" ::: "memory");
;             }
	v_cndmask_b32_dpp v55, v173, v55, vcc quad_perm:[2,3,0,1] row_mask:0xf bank_mask:0xf
	v_mul_f32_e32 v52, v52, v165
	v_mul_f32_e32 v53, v53, v165
	v_mul_f32_e32 v54, v54, v165
	v_mul_f32_e32 v55, v55, v165
	global_atomic_add_f32 v[148:149], v52, off offset:-3584
	global_atomic_add_f32 v[148:149], v53, off offset:512
	v_lshl_add_u64 v[148:149], v[148:149], 0, s[98:99]
	global_atomic_add_f32 v[148:149], v54, off offset:-3584
	global_atomic_add_f32 v[148:149], v55, off offset:512
	s_mov_b32 vcc_lo, 0x55555555
	s_mov_b32 vcc_hi, 0x55555555
	v_cndmask_b32_e32 v172, v48, v49, vcc
	v_cndmask_b32_e32 v173, v50, v51, vcc
	s_nop 0
	v_cndmask_b32_dpp v48, v172, v48, vcc quad_perm:[1,0,3,2] row_mask:0xf bank_mask:0xf
	v_cndmask_b32_dpp v50, v173, v50, vcc quad_perm:[1,0,3,2] row_mask:0xf bank_mask:0xf
	s_mov_b32 vcc_lo, 0xaaaaaaaa
	s_mov_b32 vcc_hi, 0xaaaaaaaa
	v_cndmask_b32_dpp v49, v172, v49, vcc quad_perm:[1,0,3,2] row_mask:0xf bank_mask:0xf
	v_cndmask_b32_dpp v51, v173, v51, vcc quad_perm:[1,0,3,2] row_mask:0xf bank_mask:0xf
	s_mov_b32 vcc_lo, 0x33333333
	s_mov_b32 vcc_hi, 0x33333333
	v_cndmask_b32_e32 v172, v48, v50, vcc
	v_cndmask_b32_e32 v173, v49, v51, vcc
	s_nop 0
	v_cndmask_b32_dpp v48, v172, v48, vcc quad_perm:[2,3,0,1] row_mask:0xf bank_mask:0xf
	v_cndmask_b32_dpp v49, v173, v49, vcc quad_perm:[2,3,0,1] row_mask:0xf bank_mask:0xf
	s_mov_b32 vcc_lo, 0xcccccccc
	s_mov_b32 vcc_hi, 0xcccccccc
	v_cndmask_b32_dpp v50, v172, v50, vcc quad_perm:[2,3,0,1] row_mask:0xf bank_mask:0xf
	v_cndmask_b32_dpp v51, v173, v51, vcc quad_perm:[2,3,0,1] row_mask:0xf bank_mask:0xf
	v_mul_f32_e32 v48, v48, v165
	v_mul_f32_e32 v49, v49, v165
	v_mul_f32_e32 v50, v50, v165
	v_mul_f32_e32 v51, v51, v165
	global_atomic_add_f32 v[142:143], v48, off offset:-3584
	global_atomic_add_f32 v[142:143], v49, off offset:512
	v_lshl_add_u64 v[142:143], v[142:143], 0, s[98:99]
	global_atomic_add_f32 v[142:143], v50, off offset:-3584
	global_atomic_add_f32 v[142:143], v51, off offset:512
	s_mov_b32 vcc_lo, 0x55555555
	s_mov_b32 vcc_hi, 0x55555555
	v_cndmask_b32_e32 v172, v44, v45, vcc
	v_cndmask_b32_e32 v173, v46, v47, vcc
	s_nop 0
	v_cndmask_b32_dpp v44, v172, v44, vcc quad_perm:[1,0,3,2] row_mask:0xf bank_mask:0xf
	v_cndmask_b32_dpp v46, v173, v46, vcc quad_perm:[1,0,3,2] row_mask:0xf bank_mask:0xf
	s_mov_b32 vcc_lo, 0xaaaaaaaa
	s_mov_b32 vcc_hi, 0xaaaaaaaa
	v_cndmask_b32_dpp v45, v172, v45, vcc quad_perm:[1,0,3,2] row_mask:0xf bank_mask:0xf
	v_cndmask_b32_dpp v47, v173, v47, vcc quad_perm:[1,0,3,2] row_mask:0xf bank_mask:0xf
	s_mov_b32 vcc_lo, 0x33333333
	s_mov_b32 vcc_hi, 0x33333333
	v_cndmask_b32_e32 v172, v44, v46, vcc
	v_cndmask_b32_e32 v173, v45, v47, vcc
	s_nop 0
	v_cndmask_b32_dpp v44, v172, v44, vcc quad_perm:[2,3,0,1] row_mask:0xf bank_mask:0xf
	v_cndmask_b32_dpp v45, v173, v45, vcc quad_perm:[2,3,0,1] row_mask:0xf bank_mask:0xf
	s_mov_b32 vcc_lo, 0xcccccccc
	s_mov_b32 vcc_hi, 0xcccccccc
	v_cndmask_b32_dpp v46, v172, v46, vcc quad_perm:[2,3,0,1] row_mask:0xf bank_mask:0xf
	v_cndmask_b32_dpp v47, v173, v47, vcc quad_perm:[2,3,0,1] row_mask:0xf bank_mask:0xf
	v_mul_f32_e32 v44, v44, v165
	v_mul_f32_e32 v45, v45, v165
	v_mul_f32_e32 v46, v46, v165
	v_mul_f32_e32 v47, v47, v165
	global_atomic_add_f32 v[140:141], v44, off offset:-3584
	global_atomic_add_f32 v[140:141], v45, off offset:512
	v_lshl_add_u64 v[140:141], v[140:141], 0, s[98:99]
	global_atomic_add_f32 v[140:141], v46, off offset:-3584
	global_atomic_add_f32 v[140:141], v47, off offset:512
	s_mov_b32 vcc_lo, 0x55555555
	s_mov_b32 vcc_hi, 0x55555555
	v_cndmask_b32_e32 v172, v36, v37, vcc
	v_cndmask_b32_e32 v173, v38, v39, vcc
	s_nop 0
	v_cndmask_b32_dpp v36, v172, v36, vcc quad_perm:[1,0,3,2] row_mask:0xf bank_mask:0xf
	v_cndmask_b32_dpp v38, v173, v38, vcc quad_perm:[1,0,3,2] row_mask:0xf bank_mask:0xf
	s_mov_b32 vcc_lo, 0xaaaaaaaa
	s_mov_b32 vcc_hi, 0xaaaaaaaa
	v_cndmask_b32_dpp v37, v172, v37, vcc quad_perm:[1,0,3,2] row_mask:0xf bank_mask:0xf
	v_cndmask_b32_dpp v39, v173, v39, vcc quad_perm:[1,0,3,2] row_mask:0xf bank_mask:0xf
	s_mov_b32 vcc_lo, 0x33333333
	s_mov_b32 vcc_hi, 0x33333333
	v_cndmask_b32_e32 v172, v36, v38, vcc
	v_cndmask_b32_e32 v173, v37, v39, vcc
	s_nop 0
	v_cndmask_b32_dpp v36, v172, v36, vcc quad_perm:[2,3,0,1] row_mask:0xf bank_mask:0xf
	v_cndmask_b32_dpp v37, v173, v37, vcc quad_perm:[2,3,0,1] row_mask:0xf bank_mask:0xf
	s_mov_b32 vcc_lo, 0xcccccccc
	s_mov_b32 vcc_hi, 0xcccccccc
	v_cndmask_b32_dpp v38, v172, v38, vcc quad_perm:[2,3,0,1] row_mask:0xf bank_mask:0xf
	v_cndmask_b32_dpp v39, v173, v39, vcc quad_perm:[2,3,0,1] row_mask:0xf bank_mask:0xf
	v_mul_f32_e32 v36, v36, v165
	v_mul_f32_e32 v37, v37, v165
	v_mul_f32_e32 v38, v38, v165
	v_mul_f32_e32 v39, v39, v165
	global_atomic_add_f32 v[138:139], v36, off offset:-3584
	global_atomic_add_f32 v[138:139], v37, off offset:512
	v_lshl_add_u64 v[138:139], v[138:139], 0, s[98:99]
	global_atomic_add_f32 v[138:139], v38, off offset:-3584
	global_atomic_add_f32 v[138:139], v39, off offset:512
	s_mov_b32 vcc_lo, 0x55555555
	s_mov_b32 vcc_hi, 0x55555555
	v_cndmask_b32_e32 v172, v28, v29, vcc
	v_cndmask_b32_e32 v173, v30, v31, vcc
	s_nop 0
	v_cndmask_b32_dpp v28, v172, v28, vcc quad_perm:[1,0,3,2] row_mask:0xf bank_mask:0xf
	v_cndmask_b32_dpp v30, v173, v30, vcc quad_perm:[1,0,3,2] row_mask:0xf bank_mask:0xf
	s_mov_b32 vcc_lo, 0xaaaaaaaa
	s_mov_b32 vcc_hi, 0xaaaaaaaa
	v_cndmask_b32_dpp v29, v172, v29, vcc quad_perm:[1,0,3,2] row_mask:0xf bank_mask:0xf
	v_cndmask_b32_dpp v31, v173, v31, vcc quad_perm:[1,0,3,2] row_mask:0xf bank_mask:0xf
	s_mov_b32 vcc_lo, 0x33333333
	s_mov_b32 vcc_hi, 0x33333333
	v_cndmask_b32_e32 v172, v28, v30, vcc
;     __device__ __forceinline__ void operator()(const AccT& acc, const Unit& u, int wr, int wc, int fr, int fq) const {
; #pragma unroll
;         for (int bj = 0; bj < 2; ++bj)
; #pragma unroll
;             for (int nn = 0; nn < 2; ++nn) {
;                 const int n = 256 * u.pn + 128 * bj + 32 * wc + 16 * nn + 4 * fq;
;                 const f32x4 gt = *(const f32x4*)(mod + 4 * 9216 + 2 * 1024 + n) * 0.5f;
;                 float* xb = XR + (size_t)(256 * u.pm + 64 * wr + fr) * 1024 + n;
; #pragma unroll
;                 for (int ai = 0; ai < 2; ++ai)
; #pragma unroll
;                     for (int mm = 0; mm < 4; ++mm) {
;                         float* xp = xb + (size_t)(128 * ai + 16 * mm) * 1024;
;                         const f32x4 v = acc[ai][bj][mm][nn] * gt;
; #pragma unroll
;                         for (int r = 0; r < 4; ++r) (void)__hip_atomic_fetch_add(xp + r, v[r], __ATOMIC_RELAXED, __HIP_MEMORY_SCOPE_AGENT);
;                     }
;                 asm volatile("" ::: "memory");
;             }
	v_cndmask_b32_e32 v173, v29, v31, vcc
	s_nop 0
	v_cndmask_b32_dpp v28, v172, v28, vcc quad_perm:[2,3,0,1] row_mask:0xf bank_mask:0xf
	v_cndmask_b32_dpp v29, v173, v29, vcc quad_perm:[2,3,0,1] row_mask:0xf bank_mask:0xf
	s_mov_b32 vcc_lo, 0xcccccccc
	s_mov_b32 vcc_hi, 0xcccccccc
	v_cndmask_b32_dpp v30, v172, v30, vcc quad_perm:[2,3,0,1] row_mask:0xf bank_mask:0xf
	v_cndmask_b32_dpp v31, v173, v31, vcc quad_perm:[2,3,0,1] row_mask:0xf bank_mask:0xf
	v_mul_f32_e32 v28, v28, v165
	v_mul_f32_e32 v29, v29, v165
	v_mul_f32_e32 v30, v30, v165
	v_mul_f32_e32 v31, v31, v165
	global_atomic_add_f32 v[136:137], v28, off offset:-3584
	global_atomic_add_f32 v[136:137], v29, off offset:512
	v_lshl_add_u64 v[136:137], v[136:137], 0, s[98:99]
	global_atomic_add_f32 v[136:137], v30, off offset:-3584
	global_atomic_add_f32 v[136:137], v31, off offset:512
	s_mov_b32 vcc_lo, 0x55555555
	s_mov_b32 vcc_hi, 0x55555555
	v_cndmask_b32_e32 v172, v20, v21, vcc
	v_cndmask_b32_e32 v173, v22, v23, vcc
	s_nop 0
	v_cndmask_b32_dpp v20, v172, v20, vcc quad_perm:[1,0,3,2] row_mask:0xf bank_mask:0xf
	v_cndmask_b32_dpp v22, v173, v22, vcc quad_perm:[1,0,3,2] row_mask:0xf bank_mask:0xf
	s_mov_b32 vcc_lo, 0xaaaaaaaa
	s_mov_b32 vcc_hi, 0xaaaaaaaa
	v_cndmask_b32_dpp v21, v172, v21, vcc quad_perm:[1,0,3,2] row_mask:0xf bank_mask:0xf
	v_cndmask_b32_dpp v23, v173, v23, vcc quad_perm:[1,0,3,2] row_mask:0xf bank_mask:0xf
	s_mov_b32 vcc_lo, 0x33333333
	s_mov_b32 vcc_hi, 0x33333333
	v_cndmask_b32_e32 v172, v20, v22, vcc
	v_cndmask_b32_e32 v173, v21, v23, vcc
	s_nop 0
	v_cndmask_b32_dpp v20, v172, v20, vcc quad_perm:[2,3,0,1] row_mask:0xf bank_mask:0xf
	v_cndmask_b32_dpp v21, v173, v21, vcc quad_perm:[2,3,0,1] row_mask:0xf bank_mask:0xf
	s_mov_b32 vcc_lo, 0xcccccccc
	s_mov_b32 vcc_hi, 0xcccccccc
	v_cndmask_b32_dpp v22, v172, v22, vcc quad_perm:[2,3,0,1] row_mask:0xf bank_mask:0xf
	v_cndmask_b32_dpp v23, v173, v23, vcc quad_perm:[2,3,0,1] row_mask:0xf bank_mask:0xf
	v_mul_f32_e32 v20, v20, v165
	v_mul_f32_e32 v21, v21, v165
	v_mul_f32_e32 v22, v22, v165
	v_mul_f32_e32 v23, v23, v165
	global_atomic_add_f32 v[134:135], v20, off offset:-3584
	global_atomic_add_f32 v[134:135], v21, off offset:512
	v_lshl_add_u64 v[134:135], v[134:135], 0, s[98:99]
	global_atomic_add_f32 v[134:135], v22, off offset:-3584
	global_atomic_add_f32 v[134:135], v23, off offset:512
	s_mov_b32 vcc_lo, 0x55555555
	s_mov_b32 vcc_hi, 0x55555555
	v_cndmask_b32_e32 v172, v40, v41, vcc
	v_cndmask_b32_e32 v173, v42, v43, vcc
	s_nop 0
	v_cndmask_b32_dpp v40, v172, v40, vcc quad_perm:[1,0,3,2] row_mask:0xf bank_mask:0xf
	v_cndmask_b32_dpp v42, v173, v42, vcc quad_perm:[1,0,3,2] row_mask:0xf bank_mask:0xf
	s_mov_b32 vcc_lo, 0xaaaaaaaa
	s_mov_b32 vcc_hi, 0xaaaaaaaa
	v_cndmask_b32_dpp v41, v172, v41, vcc quad_perm:[1,0,3,2] row_mask:0xf bank_mask:0xf
	v_cndmask_b32_dpp v43, v173, v43, vcc quad_perm:[1,0,3,2] row_mask:0xf bank_mask:0xf
	s_mov_b32 vcc_lo, 0x33333333
	s_mov_b32 vcc_hi, 0x33333333
	v_cndmask_b32_e32 v172, v40, v42, vcc
	v_cndmask_b32_e32 v173, v41, v43, vcc
	s_nop 0
	v_cndmask_b32_dpp v40, v172, v40, vcc quad_perm:[2,3,0,1] row_mask:0xf bank_mask:0xf
	v_cndmask_b32_dpp v41, v173, v41, vcc quad_perm:[2,3,0,1] row_mask:0xf bank_mask:0xf
	s_mov_b32 vcc_lo, 0xcccccccc
	s_mov_b32 vcc_hi, 0xcccccccc
	v_cndmask_b32_dpp v42, v172, v42, vcc quad_perm:[2,3,0,1] row_mask:0xf bank_mask:0xf
	v_cndmask_b32_dpp v43, v173, v43, vcc quad_perm:[2,3,0,1] row_mask:0xf bank_mask:0xf
	v_mul_f32_e32 v40, v40, v166
	v_mul_f32_e32 v41, v41, v166
	v_mul_f32_e32 v42, v42, v166
	v_mul_f32_e32 v43, v43, v166
	global_atomic_add_f32 v[152:153], v42, off offset:-3520
	global_atomic_add_f32 v[152:153], v43, off offset:576
	v_lshl_add_u64 v[152:153], v[152:153], 0, s[100:101]
	global_atomic_add_f32 v[152:153], v40, off offset:-3520
	global_atomic_add_f32 v[152:153], v41, off offset:576
	s_mov_b32 vcc_lo, 0x55555555
	s_mov_b32 vcc_hi, 0x55555555
	v_cndmask_b32_e32 v172, v32, v33, vcc
	v_cndmask_b32_e32 v173, v34, v35, vcc
	s_nop 0
	v_cndmask_b32_dpp v32, v172, v32, vcc quad_perm:[1,0,3,2] row_mask:0xf bank_mask:0xf
	v_cndmask_b32_dpp v34, v173, v34, vcc quad_perm:[1,0,3,2] row_mask:0xf bank_mask:0xf
	s_mov_b32 vcc_lo, 0xaaaaaaaa
	s_mov_b32 vcc_hi, 0xaaaaaaaa
	v_cndmask_b32_dpp v33, v172, v33, vcc quad_perm:[1,0,3,2] row_mask:0xf bank_mask:0xf
	v_cndmask_b32_dpp v35, v173, v35, vcc quad_perm:[1,0,3,2] row_mask:0xf bank_mask:0xf
	s_mov_b32 vcc_lo, 0x33333333
	s_mov_b32 vcc_hi, 0x33333333
	v_cndmask_b32_e32 v172, v32, v34, vcc
	v_cndmask_b32_e32 v173, v33, v35, vcc
	s_nop 0
	v_cndmask_b32_dpp v32, v172, v32, vcc quad_perm:[2,3,0,1] row_mask:0xf bank_mask:0xf
	v_cndmask_b32_dpp v33, v173, v33, vcc quad_perm:[2,3,0,1] row_mask:0xf bank_mask:0xf
	s_mov_b32 vcc_lo, 0xcccccccc
	s_mov_b32 vcc_hi, 0xcccccccc
	v_cndmask_b32_dpp v34, v172, v34, vcc quad_perm:[2,3,0,1] row_mask:0xf bank_mask:0xf
	v_cndmask_b32_dpp v35, v173, v35, vcc quad_perm:[2,3,0,1] row_mask:0xf bank_mask:0xf
	v_mul_f32_e32 v32, v32, v166
	v_mul_f32_e32 v33, v33, v166
	v_mul_f32_e32 v34, v34, v166
	v_mul_f32_e32 v35, v35, v166
	global_atomic_add_f32 v[150:151], v34, off offset:-3520
	global_atomic_add_f32 v[150:151], v35, off offset:576
	v_lshl_add_u64 v[150:151], v[150:151], 0, s[100:101]
	global_atomic_add_f32 v[150:151], v32, off offset:-3520
	global_atomic_add_f32 v[150:151], v33, off offset:576
	s_mov_b32 vcc_lo, 0x55555555
	s_mov_b32 vcc_hi, 0x55555555
	v_cndmask_b32_e32 v172, v24, v25, vcc
	v_cndmask_b32_e32 v173, v26, v27, vcc
	s_nop 0
	v_cndmask_b32_dpp v24, v172, v24, vcc quad_perm:[1,0,3,2] row_mask:0xf bank_mask:0xf
	v_cndmask_b32_dpp v26, v173, v26, vcc quad_perm:[1,0,3,2] row_mask:0xf bank_mask:0xf
;     __device__ __forceinline__ void operator()(const AccT& acc, const Unit& u, int wr, int wc, int fr, int fq) const {
; #pragma unroll
;         for (int bj = 0; bj < 2; ++bj)
; #pragma unroll
;             for (int nn = 0; nn < 2; ++nn) {
;                 const int n = 256 * u.pn + 128 * bj + 32 * wc + 16 * nn + 4 * fq;
;                 const f32x4 gt = *(const f32x4*)(mod + 4 * 9216 + 2 * 1024 + n) * 0.5f;
;                 float* xb = XR + (size_t)(256 * u.pm + 64 * wr + fr) * 1024 + n;
; #pragma unroll
;                 for (int ai = 0; ai < 2; ++ai)
; #pragma unroll
;                     for (int mm = 0; mm < 4; ++mm) {
;                         float* xp = xb + (size_t)(128 * ai + 16 * mm) * 1024;
;                         const f32x4 v = acc[ai][bj][mm][nn] * gt;
; #pragma unroll
;                         for (int r = 0; r < 4; ++r) (void)__hip_atomic_fetch_add(xp + r, v[r], __ATOMIC_RELAXED, __HIP_MEMORY_SCOPE_AGENT);
;                     }
;                 asm volatile("" ::: "memory");
;             }
	s_mov_b32 vcc_lo, 0xaaaaaaaa
	s_mov_b32 vcc_hi, 0xaaaaaaaa
	v_cndmask_b32_dpp v25, v172, v25, vcc quad_perm:[1,0,3,2] row_mask:0xf bank_mask:0xf
	v_cndmask_b32_dpp v27, v173, v27, vcc quad_perm:[1,0,3,2] row_mask:0xf bank_mask:0xf
	s_mov_b32 vcc_lo, 0x33333333
	s_mov_b32 vcc_hi, 0x33333333
	v_cndmask_b32_e32 v172, v24, v26, vcc
	v_cndmask_b32_e32 v173, v25, v27, vcc
	s_nop 0
	v_cndmask_b32_dpp v24, v172, v24, vcc quad_perm:[2,3,0,1] row_mask:0xf bank_mask:0xf
	v_cndmask_b32_dpp v25, v173, v25, vcc quad_perm:[2,3,0,1] row_mask:0xf bank_mask:0xf
	s_mov_b32 vcc_lo, 0xcccccccc
	s_mov_b32 vcc_hi, 0xcccccccc
	v_cndmask_b32_dpp v26, v172, v26, vcc quad_perm:[2,3,0,1] row_mask:0xf bank_mask:0xf
	v_cndmask_b32_dpp v27, v173, v27, vcc quad_perm:[2,3,0,1] row_mask:0xf bank_mask:0xf
	v_mul_f32_e32 v24, v24, v166
	v_mul_f32_e32 v25, v25, v166
	v_mul_f32_e32 v26, v26, v166
	v_mul_f32_e32 v27, v27, v166
	global_atomic_add_f32 v[148:149], v26, off offset:-3520
	global_atomic_add_f32 v[148:149], v27, off offset:576
	v_lshl_add_u64 v[148:149], v[148:149], 0, s[100:101]
	global_atomic_add_f32 v[148:149], v24, off offset:-3520
	global_atomic_add_f32 v[148:149], v25, off offset:576
	s_mov_b32 vcc_lo, 0x55555555
	s_mov_b32 vcc_hi, 0x55555555
	v_cndmask_b32_e32 v172, v16, v17, vcc
	v_cndmask_b32_e32 v173, v18, v19, vcc
	s_nop 0
	v_cndmask_b32_dpp v16, v172, v16, vcc quad_perm:[1,0,3,2] row_mask:0xf bank_mask:0xf
	v_cndmask_b32_dpp v18, v173, v18, vcc quad_perm:[1,0,3,2] row_mask:0xf bank_mask:0xf
	s_mov_b32 vcc_lo, 0xaaaaaaaa
	s_mov_b32 vcc_hi, 0xaaaaaaaa
	v_cndmask_b32_dpp v17, v172, v17, vcc quad_perm:[1,0,3,2] row_mask:0xf bank_mask:0xf
	v_cndmask_b32_dpp v19, v173, v19, vcc quad_perm:[1,0,3,2] row_mask:0xf bank_mask:0xf
	s_mov_b32 vcc_lo, 0x33333333
	s_mov_b32 vcc_hi, 0x33333333
	v_cndmask_b32_e32 v172, v16, v18, vcc
	v_cndmask_b32_e32 v173, v17, v19, vcc
	s_nop 0
	v_cndmask_b32_dpp v16, v172, v16, vcc quad_perm:[2,3,0,1] row_mask:0xf bank_mask:0xf
	v_cndmask_b32_dpp v17, v173, v17, vcc quad_perm:[2,3,0,1] row_mask:0xf bank_mask:0xf
	s_mov_b32 vcc_lo, 0xcccccccc
	s_mov_b32 vcc_hi, 0xcccccccc
	v_cndmask_b32_dpp v18, v172, v18, vcc quad_perm:[2,3,0,1] row_mask:0xf bank_mask:0xf
	v_cndmask_b32_dpp v19, v173, v19, vcc quad_perm:[2,3,0,1] row_mask:0xf bank_mask:0xf
	v_mul_f32_e32 v16, v16, v166
	v_mul_f32_e32 v17, v17, v166
	v_mul_f32_e32 v18, v18, v166
	v_mul_f32_e32 v19, v19, v166
	global_atomic_add_f32 v[142:143], v18, off offset:-3520
	global_atomic_add_f32 v[142:143], v19, off offset:576
	v_lshl_add_u64 v[142:143], v[142:143], 0, s[100:101]
	global_atomic_add_f32 v[142:143], v16, off offset:-3520
	global_atomic_add_f32 v[142:143], v17, off offset:576
	s_mov_b32 vcc_lo, 0x55555555
	s_mov_b32 vcc_hi, 0x55555555
	v_cndmask_b32_e32 v172, v12, v13, vcc
	v_cndmask_b32_e32 v173, v14, v15, vcc
	s_nop 0
	v_cndmask_b32_dpp v12, v172, v12, vcc quad_perm:[1,0,3,2] row_mask:0xf bank_mask:0xf
	v_cndmask_b32_dpp v14, v173, v14, vcc quad_perm:[1,0,3,2] row_mask:0xf bank_mask:0xf
	s_mov_b32 vcc_lo, 0xaaaaaaaa
	s_mov_b32 vcc_hi, 0xaaaaaaaa
	v_cndmask_b32_dpp v13, v172, v13, vcc quad_perm:[1,0,3,2] row_mask:0xf bank_mask:0xf
	v_cndmask_b32_dpp v15, v173, v15, vcc quad_perm:[1,0,3,2] row_mask:0xf bank_mask:0xf
	s_mov_b32 vcc_lo, 0x33333333
	s_mov_b32 vcc_hi, 0x33333333
	v_cndmask_b32_e32 v172, v12, v14, vcc
	v_cndmask_b32_e32 v173, v13, v15, vcc
	s_nop 0
	v_cndmask_b32_dpp v12, v172, v12, vcc quad_perm:[2,3,0,1] row_mask:0xf bank_mask:0xf
	v_cndmask_b32_dpp v13, v173, v13, vcc quad_perm:[2,3,0,1] row_mask:0xf bank_mask:0xf
	s_mov_b32 vcc_lo, 0xcccccccc
	s_mov_b32 vcc_hi, 0xcccccccc
	v_cndmask_b32_dpp v14, v172, v14, vcc quad_perm:[2,3,0,1] row_mask:0xf bank_mask:0xf
	v_cndmask_b32_dpp v15, v173, v15, vcc quad_perm:[2,3,0,1] row_mask:0xf bank_mask:0xf
	v_mul_f32_e32 v12, v12, v166
	v_mul_f32_e32 v13, v13, v166
	v_mul_f32_e32 v14, v14, v166
	v_mul_f32_e32 v15, v15, v166
	global_atomic_add_f32 v[140:141], v14, off offset:-3520
	global_atomic_add_f32 v[140:141], v15, off offset:576
	v_lshl_add_u64 v[140:141], v[140:141], 0, s[100:101]
	global_atomic_add_f32 v[140:141], v12, off offset:-3520
	global_atomic_add_f32 v[140:141], v13, off offset:576
	s_mov_b32 vcc_lo, 0x55555555
	s_mov_b32 vcc_hi, 0x55555555
	v_cndmask_b32_e32 v172, v8, v9, vcc
	v_cndmask_b32_e32 v173, v10, v11, vcc
	s_nop 0
; #define PG8_WAIT_V(n) asm volatile("s_waitcnt vmcnt(" #n ")" ::: "memory")
; #define PG8_BAR __builtin_amdgcn_s_barrier()
; template <class Epi>
; __device__ __forceinline__ void gemm_phase(PG8_LAS unsigned char* lds, const GemmD g, const Epi& E) {
;     ...
;         cur = nxt; cA = nA; cB = nB; ++ui;
;     }
;     PG8_WAIT_V(0);
;     if (wr == 0) PG8_BAR;
;     PG8_BAR;
;     __device__ __forceinline__ void operator()(const AccT& acc, const Unit& u, int wr, int wc, int fr, int fq) const {
; #pragma unroll
;         for (int bj = 0; bj < 2; ++bj)
; #pragma unroll
;             for (int nn = 0; nn < 2; ++nn) {
;                 const int n = 256 * u.pn + 128 * bj + 32 * wc + 16 * nn + 4 * fq;
;                 const f32x4 gt = *(const f32x4*)(mod + 4 * 9216 + 2 * 1024 + n) * 0.5f;
;                 float* xb = XR + (size_t)(256 * u.pm + 64 * wr + fr) * 1024 + n;
; #pragma unroll
;                 for (int ai = 0; ai < 2; ++ai)
; #pragma unroll
;                     for (int mm = 0; mm < 4; ++mm) {
;                         float* xp = xb + (size_t)(128 * ai + 16 * mm) * 1024;
;                         const f32x4 v = acc[ai][bj][mm][nn] * gt;
; #pragma unroll
;                         for (int r = 0; r < 4; ++r) (void)__hip_atomic_fetch_add(xp + r, v[r], __ATOMIC_RELAXED, __HIP_MEMORY_SCOPE_AGENT);
;                     }
;                 asm volatile("" ::: "memory");
;             }
	v_cndmask_b32_dpp v8, v172, v8, vcc quad_perm:[1,0,3,2] row_mask:0xf bank_mask:0xf
	v_cndmask_b32_dpp v10, v173, v10, vcc quad_perm:[1,0,3,2] row_mask:0xf bank_mask:0xf
	s_mov_b32 vcc_lo, 0xaaaaaaaa
	s_mov_b32 vcc_hi, 0xaaaaaaaa
	v_cndmask_b32_dpp v9, v172, v9, vcc quad_perm:[1,0,3,2] row_mask:0xf bank_mask:0xf
	v_cndmask_b32_dpp v11, v173, v11, vcc quad_perm:[1,0,3,2] row_mask:0xf bank_mask:0xf
	s_mov_b32 vcc_lo, 0x33333333
	s_mov_b32 vcc_hi, 0x33333333
	v_cndmask_b32_e32 v172, v8, v10, vcc
	v_cndmask_b32_e32 v173, v9, v11, vcc
	s_nop 0
	v_cndmask_b32_dpp v8, v172, v8, vcc quad_perm:[2,3,0,1] row_mask:0xf bank_mask:0xf
	v_cndmask_b32_dpp v9, v173, v9, vcc quad_perm:[2,3,0,1] row_mask:0xf bank_mask:0xf
	s_mov_b32 vcc_lo, 0xcccccccc
	s_mov_b32 vcc_hi, 0xcccccccc
	v_cndmask_b32_dpp v10, v172, v10, vcc quad_perm:[2,3,0,1] row_mask:0xf bank_mask:0xf
	v_cndmask_b32_dpp v11, v173, v11, vcc quad_perm:[2,3,0,1] row_mask:0xf bank_mask:0xf
	v_mul_f32_e32 v8, v8, v166
	v_mul_f32_e32 v9, v9, v166
	v_mul_f32_e32 v10, v10, v166
	v_mul_f32_e32 v11, v11, v166
	global_atomic_add_f32 v[138:139], v10, off offset:-3520
	global_atomic_add_f32 v[138:139], v11, off offset:576
	v_lshl_add_u64 v[138:139], v[138:139], 0, s[100:101]
	global_atomic_add_f32 v[138:139], v8, off offset:-3520
	global_atomic_add_f32 v[138:139], v9, off offset:576
	s_mov_b32 vcc_lo, 0x55555555
	s_mov_b32 vcc_hi, 0x55555555
	v_cndmask_b32_e32 v172, v4, v5, vcc
	v_cndmask_b32_e32 v173, v6, v7, vcc
	s_nop 0
	v_cndmask_b32_dpp v4, v172, v4, vcc quad_perm:[1,0,3,2] row_mask:0xf bank_mask:0xf
	v_cndmask_b32_dpp v6, v173, v6, vcc quad_perm:[1,0,3,2] row_mask:0xf bank_mask:0xf
	s_mov_b32 vcc_lo, 0xaaaaaaaa
	s_mov_b32 vcc_hi, 0xaaaaaaaa
	v_cndmask_b32_dpp v5, v172, v5, vcc quad_perm:[1,0,3,2] row_mask:0xf bank_mask:0xf
	v_cndmask_b32_dpp v7, v173, v7, vcc quad_perm:[1,0,3,2] row_mask:0xf bank_mask:0xf
	s_mov_b32 vcc_lo, 0x33333333
	s_mov_b32 vcc_hi, 0x33333333
	v_cndmask_b32_e32 v172, v4, v6, vcc
	v_cndmask_b32_e32 v173, v5, v7, vcc
	s_nop 0
	v_cndmask_b32_dpp v4, v172, v4, vcc quad_perm:[2,3,0,1] row_mask:0xf bank_mask:0xf
	v_cndmask_b32_dpp v5, v173, v5, vcc quad_perm:[2,3,0,1] row_mask:0xf bank_mask:0xf
	s_mov_b32 vcc_lo, 0xcccccccc
	s_mov_b32 vcc_hi, 0xcccccccc
	v_cndmask_b32_dpp v6, v172, v6, vcc quad_perm:[2,3,0,1] row_mask:0xf bank_mask:0xf
	v_cndmask_b32_dpp v7, v173, v7, vcc quad_perm:[2,3,0,1] row_mask:0xf bank_mask:0xf
	v_mul_f32_e32 v4, v4, v166
	v_mul_f32_e32 v5, v5, v166
	v_mul_f32_e32 v6, v6, v166
	v_mul_f32_e32 v7, v7, v166
	global_atomic_add_f32 v[136:137], v6, off offset:-3520
	global_atomic_add_f32 v[136:137], v7, off offset:576
	v_lshl_add_u64 v[136:137], v[136:137], 0, s[100:101]
	global_atomic_add_f32 v[136:137], v4, off offset:-3520
	global_atomic_add_f32 v[136:137], v5, off offset:576
	s_mov_b32 vcc_lo, 0x55555555
	s_mov_b32 vcc_hi, 0x55555555
	v_cndmask_b32_e32 v172, v0, v1, vcc
	v_cndmask_b32_e32 v173, v2, v3, vcc
	s_nop 0
	v_cndmask_b32_dpp v0, v172, v0, vcc quad_perm:[1,0,3,2] row_mask:0xf bank_mask:0xf
	v_cndmask_b32_dpp v2, v173, v2, vcc quad_perm:[1,0,3,2] row_mask:0xf bank_mask:0xf
	s_mov_b32 vcc_lo, 0xaaaaaaaa
	s_mov_b32 vcc_hi, 0xaaaaaaaa
	v_cndmask_b32_dpp v1, v172, v1, vcc quad_perm:[1,0,3,2] row_mask:0xf bank_mask:0xf
	v_cndmask_b32_dpp v3, v173, v3, vcc quad_perm:[1,0,3,2] row_mask:0xf bank_mask:0xf
	s_mov_b32 vcc_lo, 0x33333333
	s_mov_b32 vcc_hi, 0x33333333
	v_cndmask_b32_e32 v172, v0, v2, vcc
	v_cndmask_b32_e32 v173, v1, v3, vcc
	s_nop 0
	v_cndmask_b32_dpp v0, v172, v0, vcc quad_perm:[2,3,0,1] row_mask:0xf bank_mask:0xf
	v_cndmask_b32_dpp v1, v173, v1, vcc quad_perm:[2,3,0,1] row_mask:0xf bank_mask:0xf
	s_mov_b32 vcc_lo, 0xcccccccc
	s_mov_b32 vcc_hi, 0xcccccccc
	v_cndmask_b32_dpp v2, v172, v2, vcc quad_perm:[2,3,0,1] row_mask:0xf bank_mask:0xf
	v_cndmask_b32_dpp v3, v173, v3, vcc quad_perm:[2,3,0,1] row_mask:0xf bank_mask:0xf
	v_mul_f32_e32 v0, v0, v166
	v_mul_f32_e32 v1, v1, v166
	v_mul_f32_e32 v2, v2, v166
	v_mul_f32_e32 v3, v3, v166
	global_atomic_add_f32 v[134:135], v2, off offset:-3520
	global_atomic_add_f32 v[134:135], v3, off offset:576
	v_lshl_add_u64 v[134:135], v[134:135], 0, s[100:101]
	global_atomic_add_f32 v[134:135], v0, off offset:-3520
	global_atomic_add_f32 v[134:135], v1, off offset:576
	s_andn2_b64 vcc, exec, s[2:3]
	s_cbranch_vccnz .LBB0_371
	s_waitcnt vmcnt(0)
	s_cmpk_gt_u32 s28, 0xff
	s_cbranch_scc1 .LBB0_380
	s_barrier

; __global__ void __launch_bounds__(512, 2) mega(Params P) {
	.amdhsa_kernel _Z4mega6Params
		.amdhsa_group_segment_fixed_size 16
		.amdhsa_private_segment_fixed_size 0
		.amdhsa_kernarg_size 544
		.amdhsa_user_sgpr_count 2
		.amdhsa_user_sgpr_dispatch_ptr 0
		.amdhsa_user_sgpr_queue_ptr 0
		.amdhsa_user_sgpr_kernarg_segment_ptr 1
		.amdhsa_user_sgpr_dispatch_id 0
		.amdhsa_user_sgpr_kernarg_preload_length 0
		.amdhsa_user_sgpr_kernarg_preload_offset 0
		.amdhsa_user_sgpr_private_segment_size 0
		.amdhsa_uses_dynamic_stack 0
		.amdhsa_enable_private_segment 0
		.amdhsa_system_sgpr_workgroup_id_x 1
		.amdhsa_system_sgpr_workgroup_id_y 0
		.amdhsa_system_sgpr_workgroup_id_z 0
		.amdhsa_system_sgpr_workgroup_info 0
		.amdhsa_system_vgpr_workitem_id 2
		.amdhsa_next_free_vgpr 252
		.amdhsa_next_free_sgpr 102
		.amdhsa_accum_offset 252
		.amdhsa_reserve_vcc 1
		.amdhsa_float_round_mode_32 0
		.amdhsa_float_round_mode_16_64 0
		.amdhsa_float_denorm_mode_32 3
		.amdhsa_float_denorm_mode_16_64 3
		.amdhsa_dx10_clamp 1
		.amdhsa_ieee_mode 1
		.amdhsa_fp16_overflow 0
		.amdhsa_tg_split 0
		.amdhsa_exception_fp_ieee_invalid_op 0
		.amdhsa_exception_fp_denorm_src 0
		.amdhsa_exception_fp_ieee_div_zero 0
		.amdhsa_exception_fp_ieee_overflow 0
		.amdhsa_exception_fp_ieee_underflow 0
		.amdhsa_exception_fp_ieee_inexact 0
		.amdhsa_exception_int_div_zero 0
	.end_amdhsa_kernel

; __global__ void __launch_bounds__(512, 2) mega(Params P) {
amdhsa.kernels:
  - .agpr_count:     0
    .args:
      - .offset:         0
        .size:           288
        .value_kind:     by_value
      - .offset:         288
        .size:           4
        .value_kind:     hidden_block_count_x
      - .offset:         292
        .size:           4
        .value_kind:     hidden_block_count_y
      - .offset:         296
        .size:           4
        .value_kind:     hidden_block_count_z
      - .offset:         300
        .size:           2
        .value_kind:     hidden_group_size_x
      - .offset:         302
        .size:           2
        .value_kind:     hidden_group_size_y
      - .offset:         304
        .size:           2
        .value_kind:     hidden_group_size_z
      - .offset:         306
        .size:           2
        .value_kind:     hidden_remainder_x
      - .offset:         308
        .size:           2
        .value_kind:     hidden_remainder_y
      - .offset:         310
        .size:           2
        .value_kind:     hidden_remainder_z
      - .offset:         328
        .size:           8
        .value_kind:     hidden_global_offset_x
      - .offset:         336
        .size:           8
        .value_kind:     hidden_global_offset_y
      - .offset:         344
        .size:           8
        .value_kind:     hidden_global_offset_z
      - .offset:         352
        .size:           2
        .value_kind:     hidden_grid_dims
      - .offset:         376
        .size:           8
        .value_kind:     hidden_multigrid_sync_arg
      - .offset:         408
        .size:           4
        .value_kind:     hidden_dynamic_lds_size
    .group_segment_fixed_size: 16
    .kernarg_segment_align: 8
    .kernarg_segment_size: 544
    .language:       OpenCL C
    .language_version:
      - 2
      - 0
    .max_flat_workgroup_size: 512
    .name:           _Z4mega6Params
    .private_segment_fixed_size: 0
    .sgpr_count:     108
    .sgpr_spill_count: 72
    .symbol:         _Z4mega6Params.kd
    .uniform_work_group_size: 1
    .uses_dynamic_stack: false
    .vgpr_count:     252
    .vgpr_spill_count: 0
    .wavefront_size: 64
